# gated-merge epilogue: loads of 4 pieces hoisted together (4 groups per tile); plus all six split-K reductions sliced across arrivers
# speedup vs baseline: 1.0318x; 1.0162x over previous
.LBB0_535:
	s_lshl_b32 s28, s10, 8
	v_or_b32_e32 v174, s28, v186
	s_mov_b64 s[26:27], -1
	s_cmp_gt_i32 s8, -1
	v_ashrrev_i32_e32 v175, 31, v174
	s_cbranch_scc1 .LBB0_585
	v_lshl_add_u32 v176, s12, 8, v152
	v_mov_b64_e32 v[128:129], s[84:85]
	v_mad_i64_i32 v[128:129], s[26:27], v176, s13, v[128:129]
	v_lshl_add_u64 v[178:179], v[128:129], 0, v[174:175]
	v_mov_b64_e32 v[206:207], s[84:85]
	v_mul_lo_u32 v222, v176, s13
	v_mov_b32_e32 v223, 0
	v_lshl_add_u64 v[206:207], v[206:207], 0, v[222:223]
	v_lshl_add_u64 v[206:207], v[206:207], 0, v[174:175]
	v_lshlrev_b32_e32 v208, 12, v176
	v_mov_b32_e32 v209, 0
	v_lshl_add_u64 v[208:209], s[2:3], 0, v[208:209]
	v_lshl_add_u64 v[208:209], v[174:175], 1, v[208:209]
	v_mov_b64_e32 v[210:211], v[206:207]
	v_mov_b64_e32 v[212:213], v[208:209]
	global_load_dwordx2 v[214:215], v[210:211], off
	global_load_dwordx2 v[216:217], v[210:211], off offset:128
	global_load_dwordx4 v[190:193], v[212:213], off
	global_load_dwordx4 v[194:197], v[212:213], off offset:256
	v_mov_b32_e32 v222, 0x18000
	v_mov_b32_e32 v223, 0
	v_lshl_add_u64 v[210:211], v[210:211], 0, v[222:223]
	v_mov_b32_e32 v222, 0x10000
	v_mov_b32_e32 v223, 0
	v_lshl_add_u64 v[212:213], v[212:213], 0, v[222:223]
	global_load_dwordx2 v[218:219], v[210:211], off
	global_load_dwordx2 v[220:221], v[210:211], off offset:128
	global_load_dwordx4 v[198:201], v[212:213], off
	global_load_dwordx4 v[202:205], v[212:213], off offset:256
	s_waitcnt vmcnt(0)
	v_mov_b64_e32 v[128:129], v[214:215]
	v_ashrrev_i32_e32 v177, 31, v176
	v_lshlrev_b64 v[130:131], 12, v[176:177]
	v_lshl_add_u64 v[130:131], s[2:3], 0, v[130:131]
	v_lshl_add_u64 v[180:181], v[174:175], 1, v[130:131]
	s_and_b64 vcc, exec, s[82:83]
	v_cvt_f32_ubyte3_e32 v131, v128
	v_cvt_f32_ubyte2_e32 v130, v128
	v_cvt_f32_ubyte1_e32 v133, v128
	v_cvt_f32_ubyte0_e32 v132, v128
	v_cvt_f32_ubyte3_e32 v135, v129
	v_cvt_f32_ubyte2_e32 v134, v129
	v_cvt_f32_ubyte1_e32 v137, v129
	v_cvt_f32_ubyte0_e32 v136, v129
	v_pk_mul_f32 v[128:129], v[132:133], s[74:75] op_sel_hi:[1,0]
	v_pk_mul_f32 v[130:131], v[130:131], s[74:75] op_sel_hi:[1,0]
	v_pk_mul_f32 v[132:133], v[136:137], s[74:75] op_sel_hi:[1,0]
	v_pk_mul_f32 v[134:135], v[134:135], s[74:75] op_sel_hi:[1,0]
	v_pk_mul_f32 v[130:131], v[62:63], v[130:131]
	v_pk_mul_f32 v[128:129], v[60:61], v[128:129]
	v_pk_mul_f32 v[134:135], v[58:59], v[134:135]
	v_pk_mul_f32 v[132:133], v[56:57], v[132:133]
	s_cbranch_vccz .LBB0_594
	v_mov_b64_e32 v[136:137], v[190:191]
	v_mov_b64_e32 v[138:139], v[192:193]
	v_lshlrev_b32_e32 v140, 16, v136
	v_and_b32_e32 v141, 0xffff0000, v136
	v_lshlrev_b32_e32 v136, 16, v137
	v_and_b32_e32 v137, 0xffff0000, v137
	v_lshlrev_b32_e32 v188, 16, v138
	v_and_b32_e32 v189, 0xffff0000, v138
	v_lshlrev_b32_e32 v138, 16, v139
	v_and_b32_e32 v139, 0xffff0000, v139
	v_pk_add_f32 v[142:143], v[130:131], v[136:137]
	v_pk_add_f32 v[140:141], v[128:129], v[140:141]
	v_pk_add_f32 v[138:139], v[134:135], v[138:139]
	v_pk_add_f32 v[136:137], v[132:133], v[188:189]
	s_cbranch_execnz .LBB0_539

.LBB0_539:
	s_nop 1
	v_cvt_pk_bf16_f32 v128, v140, v141
	s_nop 1
	v_cvt_pk_bf16_f32 v129, v142, v143
	s_nop 1
	v_cvt_pk_bf16_f32 v130, v136, v137
	s_nop 1
	v_cvt_pk_bf16_f32 v131, v138, v139
	global_store_dwordx4 v[180:181], v[128:131], off
	s_nop 1
	v_mov_b64_e32 v[128:129], v[216:217]
	v_lshl_add_u64 v[178:179], v[180:181], 0, s[72:73]
	s_and_b64 vcc, exec, s[82:83]
	v_cvt_f32_ubyte3_e32 v131, v128
	v_cvt_f32_ubyte2_e32 v130, v128
	v_cvt_f32_ubyte1_e32 v133, v128
	v_cvt_f32_ubyte0_e32 v132, v128
	v_cvt_f32_ubyte3_e32 v135, v129
	v_cvt_f32_ubyte2_e32 v134, v129
	v_cvt_f32_ubyte1_e32 v137, v129
	v_cvt_f32_ubyte0_e32 v136, v129
	v_pk_mul_f32 v[128:129], v[132:133], s[74:75] op_sel_hi:[1,0]
	v_pk_mul_f32 v[130:131], v[130:131], s[74:75] op_sel_hi:[1,0]
	v_pk_mul_f32 v[132:133], v[136:137], s[74:75] op_sel_hi:[1,0]
	v_pk_mul_f32 v[134:135], v[134:135], s[74:75] op_sel_hi:[1,0]
	v_pk_mul_f32 v[130:131], v[54:55], v[130:131]
	v_pk_mul_f32 v[128:129], v[52:53], v[128:129]
	v_pk_mul_f32 v[134:135], v[50:51], v[134:135]
	v_pk_mul_f32 v[132:133], v[48:49], v[132:133]
	s_cbranch_vccz .LBB0_595
	v_mov_b64_e32 v[136:137], v[194:195]
	v_mov_b64_e32 v[138:139], v[196:197]
	v_lshlrev_b32_e32 v140, 16, v136
	v_and_b32_e32 v141, 0xffff0000, v136
	v_lshlrev_b32_e32 v136, 16, v137
	v_and_b32_e32 v137, 0xffff0000, v137
	v_lshlrev_b32_e32 v180, 16, v138
	v_and_b32_e32 v181, 0xffff0000, v138
	v_lshlrev_b32_e32 v138, 16, v139
	v_and_b32_e32 v139, 0xffff0000, v139
	v_pk_add_f32 v[142:143], v[130:131], v[136:137]
	v_pk_add_f32 v[140:141], v[128:129], v[140:141]
	v_pk_add_f32 v[138:139], v[134:135], v[138:139]
	v_pk_add_f32 v[136:137], v[132:133], v[180:181]
	s_cbranch_execnz .LBB0_542

.LBB0_542:
	s_nop 1
	v_cvt_pk_bf16_f32 v128, v140, v141
	s_nop 1
	v_cvt_pk_bf16_f32 v129, v142, v143
	s_nop 1
	v_cvt_pk_bf16_f32 v130, v136, v137
	s_nop 1
	v_cvt_pk_bf16_f32 v131, v138, v139
	global_store_dwordx4 v[178:179], v[128:131], off
	s_and_b64 vcc, exec, s[82:83]
	s_nop 0
	v_or_b32_e32 v128, 16, v176
	v_mov_b64_e32 v[130:131], s[84:85]
	v_mad_i64_i32 v[130:131], s[26:27], v128, s13, v[130:131]
	v_lshl_add_u64 v[178:179], v[130:131], 0, v[174:175]
	v_mov_b64_e32 v[130:131], v[218:219]
	v_ashrrev_i32_e32 v129, 31, v128
	v_lshlrev_b64 v[128:129], 12, v[128:129]
	v_lshl_add_u64 v[128:129], s[2:3], 0, v[128:129]
	v_lshl_add_u64 v[180:181], v[174:175], 1, v[128:129]
	v_cvt_f32_ubyte3_e32 v129, v130
	v_cvt_f32_ubyte2_e32 v128, v130
	v_cvt_f32_ubyte1_e32 v133, v130
	v_cvt_f32_ubyte0_e32 v132, v130
	v_cvt_f32_ubyte3_e32 v135, v131
	v_cvt_f32_ubyte2_e32 v134, v131
	v_cvt_f32_ubyte1_e32 v137, v131
	v_cvt_f32_ubyte0_e32 v136, v131
	v_pk_mul_f32 v[132:133], v[132:133], s[74:75] op_sel_hi:[1,0]
	v_pk_mul_f32 v[128:129], v[128:129], s[74:75] op_sel_hi:[1,0]
	v_pk_mul_f32 v[136:137], v[136:137], s[74:75] op_sel_hi:[1,0]
	v_pk_mul_f32 v[134:135], v[134:135], s[74:75] op_sel_hi:[1,0]
	v_pk_mul_f32 v[130:131], v[46:47], v[128:129]
	v_pk_mul_f32 v[128:129], v[44:45], v[132:133]
	v_pk_mul_f32 v[134:135], v[42:43], v[134:135]
	v_pk_mul_f32 v[132:133], v[40:41], v[136:137]
	s_cbranch_vccz .LBB0_596
	v_mov_b64_e32 v[136:137], v[198:199]
	v_mov_b64_e32 v[138:139], v[200:201]
	v_lshlrev_b32_e32 v140, 16, v136
	v_and_b32_e32 v141, 0xffff0000, v136
	v_lshlrev_b32_e32 v136, 16, v137
	v_and_b32_e32 v137, 0xffff0000, v137
	v_lshlrev_b32_e32 v188, 16, v138
	v_and_b32_e32 v189, 0xffff0000, v138
	v_lshlrev_b32_e32 v138, 16, v139
	v_and_b32_e32 v139, 0xffff0000, v139
	v_pk_add_f32 v[142:143], v[130:131], v[136:137]
	v_pk_add_f32 v[140:141], v[128:129], v[140:141]
	v_pk_add_f32 v[138:139], v[134:135], v[138:139]
	v_pk_add_f32 v[136:137], v[132:133], v[188:189]
	s_cbranch_execnz .LBB0_545

.LBB0_545:
	s_nop 1
	v_cvt_pk_bf16_f32 v128, v140, v141
	s_nop 1
	v_cvt_pk_bf16_f32 v129, v142, v143
	s_nop 1
	v_cvt_pk_bf16_f32 v130, v136, v137
	s_nop 1
	v_cvt_pk_bf16_f32 v131, v138, v139
	global_store_dwordx4 v[180:181], v[128:131], off
	s_nop 1
	v_mov_b64_e32 v[128:129], v[220:221]
	v_lshl_add_u64 v[178:179], v[180:181], 0, s[72:73]
	s_and_b64 vcc, exec, s[82:83]
	v_cvt_f32_ubyte3_e32 v131, v128
	v_cvt_f32_ubyte2_e32 v130, v128
	v_cvt_f32_ubyte1_e32 v133, v128
	v_cvt_f32_ubyte0_e32 v132, v128
	v_cvt_f32_ubyte3_e32 v135, v129
	v_cvt_f32_ubyte2_e32 v134, v129
	v_cvt_f32_ubyte1_e32 v137, v129
	v_cvt_f32_ubyte0_e32 v136, v129
	v_pk_mul_f32 v[128:129], v[132:133], s[74:75] op_sel_hi:[1,0]
	v_pk_mul_f32 v[130:131], v[130:131], s[74:75] op_sel_hi:[1,0]
	v_pk_mul_f32 v[132:133], v[136:137], s[74:75] op_sel_hi:[1,0]
	v_pk_mul_f32 v[134:135], v[134:135], s[74:75] op_sel_hi:[1,0]
	v_pk_mul_f32 v[130:131], v[38:39], v[130:131]
	v_pk_mul_f32 v[128:129], v[36:37], v[128:129]
	v_pk_mul_f32 v[134:135], v[34:35], v[134:135]
	v_pk_mul_f32 v[132:133], v[32:33], v[132:133]
	s_cbranch_vccz .LBB0_597
	v_mov_b64_e32 v[136:137], v[202:203]
	v_mov_b64_e32 v[138:139], v[204:205]
	v_lshlrev_b32_e32 v140, 16, v136
	v_and_b32_e32 v141, 0xffff0000, v136
	v_lshlrev_b32_e32 v136, 16, v137
	v_and_b32_e32 v137, 0xffff0000, v137
	v_lshlrev_b32_e32 v180, 16, v138
	v_and_b32_e32 v181, 0xffff0000, v138
	v_lshlrev_b32_e32 v138, 16, v139
	v_and_b32_e32 v139, 0xffff0000, v139
	v_pk_add_f32 v[142:143], v[130:131], v[136:137]
	v_pk_add_f32 v[140:141], v[128:129], v[140:141]
	v_pk_add_f32 v[138:139], v[134:135], v[138:139]
	v_pk_add_f32 v[136:137], v[132:133], v[180:181]
	s_cbranch_execnz .LBB0_548

.LBB0_548:
	s_nop 1
	v_cvt_pk_bf16_f32 v128, v140, v141
	s_nop 1
	v_cvt_pk_bf16_f32 v129, v142, v143
	s_nop 1
	v_cvt_pk_bf16_f32 v130, v136, v137
	s_nop 1
	v_cvt_pk_bf16_f32 v131, v138, v139
	global_store_dwordx4 v[178:179], v[128:131], off
	s_and_b64 vcc, exec, s[82:83]
	s_nop 0
	v_or_b32_e32 v128, 32, v176
	v_mov_b64_e32 v[130:131], s[84:85]
	v_mad_i64_i32 v[130:131], s[26:27], v128, s13, v[130:131]
	v_lshl_add_u64 v[178:179], v[130:131], 0, v[174:175]
	v_mov_b64_e32 v[210:211], v[206:207]
	v_mov_b64_e32 v[212:213], v[208:209]
	v_mov_b32_e32 v222, 0x30000
	v_mov_b32_e32 v223, 0
	v_lshl_add_u64 v[210:211], v[210:211], 0, v[222:223]
	v_mov_b32_e32 v222, 0x20000
	v_mov_b32_e32 v223, 0
	v_lshl_add_u64 v[212:213], v[212:213], 0, v[222:223]
	global_load_dwordx2 v[214:215], v[210:211], off
	global_load_dwordx2 v[216:217], v[210:211], off offset:128
	global_load_dwordx4 v[190:193], v[212:213], off
	global_load_dwordx4 v[194:197], v[212:213], off offset:256
	v_mov_b32_e32 v222, 0x18000
	v_mov_b32_e32 v223, 0
	v_lshl_add_u64 v[210:211], v[210:211], 0, v[222:223]
	v_mov_b32_e32 v222, 0x10000
	v_mov_b32_e32 v223, 0
	v_lshl_add_u64 v[212:213], v[212:213], 0, v[222:223]
	global_load_dwordx2 v[218:219], v[210:211], off
	global_load_dwordx2 v[220:221], v[210:211], off offset:128
	global_load_dwordx4 v[198:201], v[212:213], off
	global_load_dwordx4 v[202:205], v[212:213], off offset:256
	s_waitcnt vmcnt(0)
	v_mov_b64_e32 v[130:131], v[214:215]
	v_ashrrev_i32_e32 v129, 31, v128
	v_lshlrev_b64 v[128:129], 12, v[128:129]
	v_lshl_add_u64 v[128:129], s[2:3], 0, v[128:129]
	v_lshl_add_u64 v[180:181], v[174:175], 1, v[128:129]
	v_cvt_f32_ubyte3_e32 v129, v130
	v_cvt_f32_ubyte2_e32 v128, v130
	v_cvt_f32_ubyte1_e32 v133, v130
	v_cvt_f32_ubyte0_e32 v132, v130
	v_cvt_f32_ubyte3_e32 v135, v131
	v_cvt_f32_ubyte2_e32 v134, v131
	v_cvt_f32_ubyte1_e32 v137, v131
	v_cvt_f32_ubyte0_e32 v136, v131
	v_pk_mul_f32 v[132:133], v[132:133], s[74:75] op_sel_hi:[1,0]
	v_pk_mul_f32 v[128:129], v[128:129], s[74:75] op_sel_hi:[1,0]
	v_pk_mul_f32 v[136:137], v[136:137], s[74:75] op_sel_hi:[1,0]
	v_pk_mul_f32 v[134:135], v[134:135], s[74:75] op_sel_hi:[1,0]
	v_pk_mul_f32 v[130:131], v[30:31], v[128:129]
	v_pk_mul_f32 v[128:129], v[28:29], v[132:133]
	v_pk_mul_f32 v[134:135], v[26:27], v[134:135]
	v_pk_mul_f32 v[132:133], v[24:25], v[136:137]
	s_cbranch_vccz .LBB0_598
	v_mov_b64_e32 v[136:137], v[190:191]
	v_mov_b64_e32 v[138:139], v[192:193]
	v_lshlrev_b32_e32 v140, 16, v136
	v_and_b32_e32 v141, 0xffff0000, v136
	v_lshlrev_b32_e32 v136, 16, v137
	v_and_b32_e32 v137, 0xffff0000, v137
	v_lshlrev_b32_e32 v188, 16, v138
	v_and_b32_e32 v189, 0xffff0000, v138
	v_lshlrev_b32_e32 v138, 16, v139
	v_and_b32_e32 v139, 0xffff0000, v139
	v_pk_add_f32 v[142:143], v[130:131], v[136:137]
	v_pk_add_f32 v[140:141], v[128:129], v[140:141]
	v_pk_add_f32 v[138:139], v[134:135], v[138:139]
	v_pk_add_f32 v[136:137], v[132:133], v[188:189]
	s_cbranch_execnz .LBB0_551

.LBB0_551:
	s_nop 1
	v_cvt_pk_bf16_f32 v128, v140, v141
	s_nop 1
	v_cvt_pk_bf16_f32 v129, v142, v143
	s_nop 1
	v_cvt_pk_bf16_f32 v130, v136, v137
	s_nop 1
	v_cvt_pk_bf16_f32 v131, v138, v139
	global_store_dwordx4 v[180:181], v[128:131], off
	s_nop 1
	v_mov_b64_e32 v[128:129], v[216:217]
	v_lshl_add_u64 v[178:179], v[180:181], 0, s[72:73]
	s_and_b64 vcc, exec, s[82:83]
	v_cvt_f32_ubyte3_e32 v131, v128
	v_cvt_f32_ubyte2_e32 v130, v128
	v_cvt_f32_ubyte1_e32 v133, v128
	v_cvt_f32_ubyte0_e32 v132, v128
	v_cvt_f32_ubyte3_e32 v135, v129
	v_cvt_f32_ubyte2_e32 v134, v129
	v_cvt_f32_ubyte1_e32 v137, v129
	v_cvt_f32_ubyte0_e32 v136, v129
	v_pk_mul_f32 v[128:129], v[132:133], s[74:75] op_sel_hi:[1,0]
	v_pk_mul_f32 v[130:131], v[130:131], s[74:75] op_sel_hi:[1,0]
	v_pk_mul_f32 v[132:133], v[136:137], s[74:75] op_sel_hi:[1,0]
	v_pk_mul_f32 v[134:135], v[134:135], s[74:75] op_sel_hi:[1,0]
	v_pk_mul_f32 v[130:131], v[22:23], v[130:131]
	v_pk_mul_f32 v[128:129], v[20:21], v[128:129]
	v_pk_mul_f32 v[134:135], v[18:19], v[134:135]
	v_pk_mul_f32 v[132:133], v[16:17], v[132:133]
	s_cbranch_vccz .LBB0_599
	v_mov_b64_e32 v[136:137], v[194:195]
	v_mov_b64_e32 v[138:139], v[196:197]
	v_lshlrev_b32_e32 v140, 16, v136
	v_and_b32_e32 v141, 0xffff0000, v136
	v_lshlrev_b32_e32 v136, 16, v137
	v_and_b32_e32 v137, 0xffff0000, v137
	v_lshlrev_b32_e32 v180, 16, v138
	v_and_b32_e32 v181, 0xffff0000, v138
	v_lshlrev_b32_e32 v138, 16, v139
	v_and_b32_e32 v139, 0xffff0000, v139
	v_pk_add_f32 v[142:143], v[130:131], v[136:137]
	v_pk_add_f32 v[140:141], v[128:129], v[140:141]
	v_pk_add_f32 v[138:139], v[134:135], v[138:139]
	v_pk_add_f32 v[136:137], v[132:133], v[180:181]
	s_cbranch_execnz .LBB0_554

.LBB0_554:
	s_nop 1
	v_cvt_pk_bf16_f32 v128, v140, v141
	s_nop 1
	v_cvt_pk_bf16_f32 v129, v142, v143
	s_nop 1
	v_cvt_pk_bf16_f32 v130, v136, v137
	s_nop 1
	v_cvt_pk_bf16_f32 v131, v138, v139
	global_store_dwordx4 v[178:179], v[128:131], off
	s_and_b64 vcc, exec, s[82:83]
	s_nop 0
	v_or_b32_e32 v128, 48, v176
	v_mov_b64_e32 v[130:131], s[84:85]
	v_mad_i64_i32 v[130:131], s[26:27], v128, s13, v[130:131]
	v_lshl_add_u64 v[178:179], v[130:131], 0, v[174:175]
	v_mov_b64_e32 v[130:131], v[218:219]
	v_ashrrev_i32_e32 v129, 31, v128
	v_lshlrev_b64 v[128:129], 12, v[128:129]
	v_lshl_add_u64 v[128:129], s[2:3], 0, v[128:129]
	v_lshl_add_u64 v[180:181], v[174:175], 1, v[128:129]
	v_cvt_f32_ubyte3_e32 v129, v130
	v_cvt_f32_ubyte2_e32 v128, v130
	v_cvt_f32_ubyte1_e32 v133, v130
	v_cvt_f32_ubyte0_e32 v132, v130
	v_cvt_f32_ubyte3_e32 v135, v131
	v_cvt_f32_ubyte2_e32 v134, v131
	v_cvt_f32_ubyte1_e32 v137, v131
	v_cvt_f32_ubyte0_e32 v136, v131
	v_pk_mul_f32 v[132:133], v[132:133], s[74:75] op_sel_hi:[1,0]
	v_pk_mul_f32 v[128:129], v[128:129], s[74:75] op_sel_hi:[1,0]
	v_pk_mul_f32 v[136:137], v[136:137], s[74:75] op_sel_hi:[1,0]
	v_pk_mul_f32 v[134:135], v[134:135], s[74:75] op_sel_hi:[1,0]
	v_pk_mul_f32 v[130:131], v[14:15], v[128:129]
	v_pk_mul_f32 v[128:129], v[12:13], v[132:133]
	v_pk_mul_f32 v[134:135], v[10:11], v[134:135]
	v_pk_mul_f32 v[132:133], v[8:9], v[136:137]
	s_cbranch_vccz .LBB0_600
	v_mov_b64_e32 v[136:137], v[198:199]
	v_mov_b64_e32 v[138:139], v[200:201]
	v_lshlrev_b32_e32 v140, 16, v136
	v_and_b32_e32 v141, 0xffff0000, v136
	v_lshlrev_b32_e32 v136, 16, v137
	v_and_b32_e32 v137, 0xffff0000, v137
	v_lshlrev_b32_e32 v188, 16, v138
	v_and_b32_e32 v189, 0xffff0000, v138
	v_lshlrev_b32_e32 v138, 16, v139
	v_and_b32_e32 v139, 0xffff0000, v139
	v_pk_add_f32 v[142:143], v[130:131], v[136:137]
	v_pk_add_f32 v[140:141], v[128:129], v[140:141]
	v_pk_add_f32 v[138:139], v[134:135], v[138:139]
	v_pk_add_f32 v[136:137], v[132:133], v[188:189]
	s_cbranch_execnz .LBB0_557

.LBB0_557:
	s_nop 1
	v_cvt_pk_bf16_f32 v128, v140, v141
	s_nop 1
	v_cvt_pk_bf16_f32 v129, v142, v143
	s_nop 1
	v_cvt_pk_bf16_f32 v130, v136, v137
	s_nop 1
	v_cvt_pk_bf16_f32 v131, v138, v139
	global_store_dwordx4 v[180:181], v[128:131], off
	s_nop 1
	v_mov_b64_e32 v[128:129], v[220:221]
	v_lshl_add_u64 v[178:179], v[180:181], 0, s[72:73]
	s_and_b64 vcc, exec, s[82:83]
	v_cvt_f32_ubyte3_e32 v131, v128
	v_cvt_f32_ubyte2_e32 v130, v128
	v_cvt_f32_ubyte1_e32 v133, v128
	v_cvt_f32_ubyte0_e32 v132, v128
	v_cvt_f32_ubyte3_e32 v135, v129
	v_cvt_f32_ubyte2_e32 v134, v129
	v_cvt_f32_ubyte1_e32 v137, v129
	v_cvt_f32_ubyte0_e32 v136, v129
	v_pk_mul_f32 v[128:129], v[132:133], s[74:75] op_sel_hi:[1,0]
	v_pk_mul_f32 v[130:131], v[130:131], s[74:75] op_sel_hi:[1,0]
	v_pk_mul_f32 v[132:133], v[136:137], s[74:75] op_sel_hi:[1,0]
	v_pk_mul_f32 v[134:135], v[134:135], s[74:75] op_sel_hi:[1,0]
	v_pk_mul_f32 v[130:131], v[6:7], v[130:131]
	v_pk_mul_f32 v[128:129], v[4:5], v[128:129]
	v_pk_mul_f32 v[134:135], v[2:3], v[134:135]
	v_pk_mul_f32 v[132:133], v[0:1], v[132:133]
	s_cbranch_vccz .LBB0_601
	v_mov_b64_e32 v[136:137], v[202:203]
	v_mov_b64_e32 v[138:139], v[204:205]
	v_lshlrev_b32_e32 v140, 16, v136
	v_and_b32_e32 v141, 0xffff0000, v136
	v_lshlrev_b32_e32 v136, 16, v137
	v_and_b32_e32 v137, 0xffff0000, v137
	v_lshlrev_b32_e32 v180, 16, v138
	v_and_b32_e32 v181, 0xffff0000, v138
	v_lshlrev_b32_e32 v138, 16, v139
	v_and_b32_e32 v139, 0xffff0000, v139
	v_pk_add_f32 v[142:143], v[130:131], v[136:137]
	v_pk_add_f32 v[140:141], v[128:129], v[140:141]
	v_pk_add_f32 v[138:139], v[134:135], v[138:139]
	v_pk_add_f32 v[136:137], v[132:133], v[180:181]
	s_cbranch_execnz .LBB0_560

.LBB0_560:
	s_nop 1
	v_cvt_pk_bf16_f32 v128, v140, v141
	s_nop 1
	v_cvt_pk_bf16_f32 v129, v142, v143
	s_nop 1
	v_cvt_pk_bf16_f32 v130, v136, v137
	s_nop 1
	v_cvt_pk_bf16_f32 v131, v138, v139
	global_store_dwordx4 v[178:179], v[128:131], off
	v_mov_b64_e32 v[132:133], s[84:85]
	s_and_b64 vcc, exec, s[82:83]
	v_add_u32_e32 v128, 0x80, v176
	v_ashrrev_i32_e32 v129, 31, v128
	v_lshlrev_b64 v[130:131], 12, v[128:129]
	v_mad_i64_i32 v[128:129], s[26:27], v128, s13, v[132:133]
	v_lshl_add_u64 v[138:139], v[128:129], 0, v[174:175]
	v_mov_b64_e32 v[210:211], v[206:207]
	v_mov_b64_e32 v[212:213], v[208:209]
	v_mov_b32_e32 v222, 0xc0000
	v_mov_b32_e32 v223, 0
	v_lshl_add_u64 v[210:211], v[210:211], 0, v[222:223]
	v_mov_b32_e32 v222, 0x80000
	v_mov_b32_e32 v223, 0
	v_lshl_add_u64 v[212:213], v[212:213], 0, v[222:223]
	global_load_dwordx2 v[214:215], v[210:211], off
	global_load_dwordx2 v[216:217], v[210:211], off offset:128
	global_load_dwordx4 v[190:193], v[212:213], off
	global_load_dwordx4 v[194:197], v[212:213], off offset:256
	v_mov_b32_e32 v222, 0x18000
	v_mov_b32_e32 v223, 0
	v_lshl_add_u64 v[210:211], v[210:211], 0, v[222:223]
	v_mov_b32_e32 v222, 0x10000
	v_mov_b32_e32 v223, 0
	v_lshl_add_u64 v[212:213], v[212:213], 0, v[222:223]
	global_load_dwordx2 v[218:219], v[210:211], off
	global_load_dwordx2 v[220:221], v[210:211], off offset:128
	global_load_dwordx4 v[198:201], v[212:213], off
	global_load_dwordx4 v[202:205], v[212:213], off offset:256
	s_waitcnt vmcnt(0)
	v_mov_b64_e32 v[128:129], v[214:215]
	v_cvt_f32_ubyte1_e32 v135, v128
	v_cvt_f32_ubyte0_e32 v134, v128
	v_cvt_f32_ubyte3_e32 v133, v128
	v_cvt_f32_ubyte2_e32 v132, v128
	v_pk_mul_f32 v[134:135], v[134:135], s[74:75] op_sel_hi:[1,0]
	v_pk_mul_f32 v[132:133], v[132:133], s[74:75] op_sel_hi:[1,0]
	v_pk_mul_f32 v[124:125], v[124:125], v[134:135]
	v_cvt_f32_ubyte1_e32 v135, v129
	v_cvt_f32_ubyte0_e32 v134, v129
	v_pk_mul_f32 v[126:127], v[126:127], v[132:133]
	v_cvt_f32_ubyte3_e32 v133, v129
	v_cvt_f32_ubyte2_e32 v132, v129
	v_pk_mul_f32 v[128:129], v[134:135], s[74:75] op_sel_hi:[1,0]
	v_pk_mul_f32 v[132:133], v[132:133], s[74:75] op_sel_hi:[1,0]
	v_pk_mul_f32 v[120:121], v[120:121], v[128:129]
	v_lshl_add_u64 v[128:129], s[2:3], 0, v[130:131]
	v_pk_mul_f32 v[122:123], v[122:123], v[132:133]
	v_lshl_add_u64 v[136:137], v[174:175], 1, v[128:129]
	s_cbranch_vccz .LBB0_602
	v_mov_b64_e32 v[128:129], v[190:191]
	v_mov_b64_e32 v[130:131], v[192:193]
	v_lshlrev_b32_e32 v132, 16, v128
	v_and_b32_e32 v133, 0xffff0000, v128
	v_lshlrev_b32_e32 v128, 16, v129
	v_and_b32_e32 v129, 0xffff0000, v129
	v_lshlrev_b32_e32 v140, 16, v130
	v_and_b32_e32 v141, 0xffff0000, v130
	v_lshlrev_b32_e32 v130, 16, v131
	v_and_b32_e32 v131, 0xffff0000, v131
	v_pk_add_f32 v[134:135], v[126:127], v[128:129]
	v_pk_add_f32 v[132:133], v[124:125], v[132:133]
	v_pk_add_f32 v[130:131], v[122:123], v[130:131]
	v_pk_add_f32 v[128:129], v[120:121], v[140:141]
	s_cbranch_execnz .LBB0_563

.LBB0_563:
	s_nop 1
	v_cvt_pk_bf16_f32 v120, v132, v133
	s_nop 1
	v_cvt_pk_bf16_f32 v121, v134, v135
	s_nop 1
	v_cvt_pk_bf16_f32 v122, v128, v129
	s_nop 1
	v_cvt_pk_bf16_f32 v123, v130, v131
	global_store_dwordx4 v[136:137], v[120:123], off
	s_nop 1
	v_mov_b64_e32 v[120:121], v[216:217]
	v_lshl_add_u64 v[128:129], v[136:137], 0, s[72:73]
	s_and_b64 vcc, exec, s[82:83]
	v_cvt_f32_ubyte3_e32 v123, v120
	v_cvt_f32_ubyte2_e32 v122, v120
	v_cvt_f32_ubyte1_e32 v125, v120
	v_cvt_f32_ubyte0_e32 v124, v120
	v_cvt_f32_ubyte3_e32 v127, v121
	v_cvt_f32_ubyte2_e32 v126, v121
	v_cvt_f32_ubyte1_e32 v131, v121
	v_cvt_f32_ubyte0_e32 v130, v121
	v_pk_mul_f32 v[120:121], v[124:125], s[74:75] op_sel_hi:[1,0]
	v_pk_mul_f32 v[122:123], v[122:123], s[74:75] op_sel_hi:[1,0]
	v_pk_mul_f32 v[124:125], v[130:131], s[74:75] op_sel_hi:[1,0]
	v_pk_mul_f32 v[126:127], v[126:127], s[74:75] op_sel_hi:[1,0]
	v_pk_mul_f32 v[118:119], v[118:119], v[122:123]
	v_pk_mul_f32 v[116:117], v[116:117], v[120:121]
	v_pk_mul_f32 v[114:115], v[114:115], v[126:127]
	v_pk_mul_f32 v[112:113], v[112:113], v[124:125]
	s_cbranch_vccz .LBB0_603
	v_mov_b64_e32 v[120:121], v[194:195]
	v_mov_b64_e32 v[122:123], v[196:197]
	v_lshlrev_b32_e32 v124, 16, v120
	v_and_b32_e32 v125, 0xffff0000, v120
	v_lshlrev_b32_e32 v120, 16, v121
	v_and_b32_e32 v121, 0xffff0000, v121
	v_lshlrev_b32_e32 v130, 16, v122
	v_and_b32_e32 v131, 0xffff0000, v122
	v_lshlrev_b32_e32 v122, 16, v123
	v_and_b32_e32 v123, 0xffff0000, v123
	v_pk_add_f32 v[126:127], v[118:119], v[120:121]
	v_pk_add_f32 v[124:125], v[116:117], v[124:125]
	v_pk_add_f32 v[122:123], v[114:115], v[122:123]
	v_pk_add_f32 v[120:121], v[112:113], v[130:131]
	s_cbranch_execnz .LBB0_566

.LBB0_566:
	s_nop 1
	v_cvt_pk_bf16_f32 v112, v124, v125
	s_nop 1
	v_cvt_pk_bf16_f32 v113, v126, v127
	s_nop 1
	v_cvt_pk_bf16_f32 v114, v120, v121
	s_nop 1
	v_cvt_pk_bf16_f32 v115, v122, v123
	global_store_dwordx4 v[128:129], v[112:115], off
	v_mov_b64_e32 v[116:117], s[84:85]
	s_and_b64 vcc, exec, s[82:83]
	v_add_u32_e32 v112, 0x90, v176
	v_ashrrev_i32_e32 v113, 31, v112
	v_lshlrev_b64 v[114:115], 12, v[112:113]
	v_mad_i64_i32 v[112:113], s[26:27], v112, s13, v[116:117]
	v_lshl_add_u64 v[122:123], v[112:113], 0, v[174:175]
	v_mov_b64_e32 v[112:113], v[218:219]
	v_cvt_f32_ubyte1_e32 v119, v112
	v_cvt_f32_ubyte0_e32 v118, v112
	v_cvt_f32_ubyte3_e32 v117, v112
	v_cvt_f32_ubyte2_e32 v116, v112
	v_pk_mul_f32 v[118:119], v[118:119], s[74:75] op_sel_hi:[1,0]
	v_pk_mul_f32 v[116:117], v[116:117], s[74:75] op_sel_hi:[1,0]
	v_pk_mul_f32 v[108:109], v[108:109], v[118:119]
	v_cvt_f32_ubyte1_e32 v119, v113
	v_cvt_f32_ubyte0_e32 v118, v113
	v_pk_mul_f32 v[110:111], v[110:111], v[116:117]
	v_cvt_f32_ubyte3_e32 v117, v113
	v_cvt_f32_ubyte2_e32 v116, v113
	v_pk_mul_f32 v[112:113], v[118:119], s[74:75] op_sel_hi:[1,0]
	v_pk_mul_f32 v[116:117], v[116:117], s[74:75] op_sel_hi:[1,0]
	v_pk_mul_f32 v[104:105], v[104:105], v[112:113]
	v_lshl_add_u64 v[112:113], s[2:3], 0, v[114:115]
	v_pk_mul_f32 v[106:107], v[106:107], v[116:117]
	v_lshl_add_u64 v[120:121], v[174:175], 1, v[112:113]
	s_cbranch_vccz .LBB0_604
	v_mov_b64_e32 v[112:113], v[198:199]
	v_mov_b64_e32 v[114:115], v[200:201]
	v_lshlrev_b32_e32 v116, 16, v112
	v_and_b32_e32 v117, 0xffff0000, v112
	v_lshlrev_b32_e32 v112, 16, v113
	v_and_b32_e32 v113, 0xffff0000, v113
	v_lshlrev_b32_e32 v124, 16, v114
	v_and_b32_e32 v125, 0xffff0000, v114
	v_lshlrev_b32_e32 v114, 16, v115
	v_and_b32_e32 v115, 0xffff0000, v115
	v_pk_add_f32 v[118:119], v[110:111], v[112:113]
	v_pk_add_f32 v[116:117], v[108:109], v[116:117]
	v_pk_add_f32 v[114:115], v[106:107], v[114:115]
	v_pk_add_f32 v[112:113], v[104:105], v[124:125]
	s_cbranch_execnz .LBB0_569

.LBB0_569:
	s_nop 1
	v_cvt_pk_bf16_f32 v104, v116, v117
	s_nop 1
	v_cvt_pk_bf16_f32 v105, v118, v119
	s_nop 1
	v_cvt_pk_bf16_f32 v106, v112, v113
	s_nop 1
	v_cvt_pk_bf16_f32 v107, v114, v115
	global_store_dwordx4 v[120:121], v[104:107], off
	s_nop 1
	v_mov_b64_e32 v[104:105], v[220:221]
	v_lshl_add_u64 v[112:113], v[120:121], 0, s[72:73]
	s_and_b64 vcc, exec, s[82:83]
	v_cvt_f32_ubyte3_e32 v107, v104
	v_cvt_f32_ubyte2_e32 v106, v104
	v_cvt_f32_ubyte1_e32 v109, v104
	v_cvt_f32_ubyte0_e32 v108, v104
	v_cvt_f32_ubyte3_e32 v111, v105
	v_cvt_f32_ubyte2_e32 v110, v105
	v_cvt_f32_ubyte1_e32 v115, v105
	v_cvt_f32_ubyte0_e32 v114, v105
	v_pk_mul_f32 v[104:105], v[108:109], s[74:75] op_sel_hi:[1,0]
	v_pk_mul_f32 v[106:107], v[106:107], s[74:75] op_sel_hi:[1,0]
	v_pk_mul_f32 v[108:109], v[114:115], s[74:75] op_sel_hi:[1,0]
	v_pk_mul_f32 v[110:111], v[110:111], s[74:75] op_sel_hi:[1,0]
	v_pk_mul_f32 v[102:103], v[102:103], v[106:107]
	v_pk_mul_f32 v[100:101], v[100:101], v[104:105]
	v_pk_mul_f32 v[98:99], v[98:99], v[110:111]
	v_pk_mul_f32 v[96:97], v[96:97], v[108:109]
	s_cbranch_vccz .LBB0_605
	v_mov_b64_e32 v[104:105], v[202:203]
	v_mov_b64_e32 v[106:107], v[204:205]
	v_lshlrev_b32_e32 v108, 16, v104
	v_and_b32_e32 v109, 0xffff0000, v104
	v_lshlrev_b32_e32 v104, 16, v105
	v_and_b32_e32 v105, 0xffff0000, v105
	v_lshlrev_b32_e32 v114, 16, v106
	v_and_b32_e32 v115, 0xffff0000, v106
	v_lshlrev_b32_e32 v106, 16, v107
	v_and_b32_e32 v107, 0xffff0000, v107
	v_pk_add_f32 v[110:111], v[102:103], v[104:105]
	v_pk_add_f32 v[108:109], v[100:101], v[108:109]
	v_pk_add_f32 v[106:107], v[98:99], v[106:107]
	v_pk_add_f32 v[104:105], v[96:97], v[114:115]
	s_cbranch_execnz .LBB0_572

.LBB0_572:
	s_nop 1
	v_cvt_pk_bf16_f32 v96, v108, v109
	s_nop 1
	v_cvt_pk_bf16_f32 v97, v110, v111
	s_nop 1
	v_cvt_pk_bf16_f32 v98, v104, v105
	s_nop 1
	v_cvt_pk_bf16_f32 v99, v106, v107
	global_store_dwordx4 v[112:113], v[96:99], off
	v_mov_b64_e32 v[100:101], s[84:85]
	s_and_b64 vcc, exec, s[82:83]
	v_add_u32_e32 v96, 0xa0, v176
	v_ashrrev_i32_e32 v97, 31, v96
	v_lshlrev_b64 v[98:99], 12, v[96:97]
	v_mad_i64_i32 v[96:97], s[26:27], v96, s13, v[100:101]
	v_lshl_add_u64 v[106:107], v[96:97], 0, v[174:175]
	v_mov_b64_e32 v[210:211], v[206:207]
	v_mov_b64_e32 v[212:213], v[208:209]
	v_mov_b32_e32 v222, 0xf0000
	v_mov_b32_e32 v223, 0
	v_lshl_add_u64 v[210:211], v[210:211], 0, v[222:223]
	v_mov_b32_e32 v222, 0xa0000
	v_mov_b32_e32 v223, 0
	v_lshl_add_u64 v[212:213], v[212:213], 0, v[222:223]
	global_load_dwordx2 v[214:215], v[210:211], off
	global_load_dwordx2 v[216:217], v[210:211], off offset:128
	global_load_dwordx4 v[190:193], v[212:213], off
	global_load_dwordx4 v[194:197], v[212:213], off offset:256
	v_mov_b32_e32 v222, 0x18000
	v_mov_b32_e32 v223, 0
	v_lshl_add_u64 v[210:211], v[210:211], 0, v[222:223]
	v_mov_b32_e32 v222, 0x10000
	v_mov_b32_e32 v223, 0
	v_lshl_add_u64 v[212:213], v[212:213], 0, v[222:223]
	global_load_dwordx2 v[218:219], v[210:211], off
	global_load_dwordx2 v[220:221], v[210:211], off offset:128
	global_load_dwordx4 v[198:201], v[212:213], off
	global_load_dwordx4 v[202:205], v[212:213], off offset:256
	s_waitcnt vmcnt(0)
	v_mov_b64_e32 v[96:97], v[214:215]
	v_cvt_f32_ubyte1_e32 v103, v96
	v_cvt_f32_ubyte0_e32 v102, v96
	v_cvt_f32_ubyte3_e32 v101, v96
	v_cvt_f32_ubyte2_e32 v100, v96
	v_pk_mul_f32 v[102:103], v[102:103], s[74:75] op_sel_hi:[1,0]
	v_pk_mul_f32 v[100:101], v[100:101], s[74:75] op_sel_hi:[1,0]
	v_pk_mul_f32 v[92:93], v[92:93], v[102:103]
	v_cvt_f32_ubyte1_e32 v103, v97
	v_cvt_f32_ubyte0_e32 v102, v97
	v_pk_mul_f32 v[94:95], v[94:95], v[100:101]
	v_cvt_f32_ubyte3_e32 v101, v97
	v_cvt_f32_ubyte2_e32 v100, v97
	v_pk_mul_f32 v[96:97], v[102:103], s[74:75] op_sel_hi:[1,0]
	v_pk_mul_f32 v[100:101], v[100:101], s[74:75] op_sel_hi:[1,0]
	v_pk_mul_f32 v[88:89], v[88:89], v[96:97]
	v_lshl_add_u64 v[96:97], s[2:3], 0, v[98:99]
	v_pk_mul_f32 v[90:91], v[90:91], v[100:101]
	v_lshl_add_u64 v[104:105], v[174:175], 1, v[96:97]
	s_cbranch_vccz .LBB0_606
	v_mov_b64_e32 v[96:97], v[190:191]
	v_mov_b64_e32 v[98:99], v[192:193]
	v_lshlrev_b32_e32 v100, 16, v96
	v_and_b32_e32 v101, 0xffff0000, v96
	v_lshlrev_b32_e32 v96, 16, v97
	v_and_b32_e32 v97, 0xffff0000, v97
	v_lshlrev_b32_e32 v108, 16, v98
	v_and_b32_e32 v109, 0xffff0000, v98
	v_lshlrev_b32_e32 v98, 16, v99
	v_and_b32_e32 v99, 0xffff0000, v99
	v_pk_add_f32 v[102:103], v[94:95], v[96:97]
	v_pk_add_f32 v[100:101], v[92:93], v[100:101]
	v_pk_add_f32 v[98:99], v[90:91], v[98:99]
	v_pk_add_f32 v[96:97], v[88:89], v[108:109]
	s_cbranch_execnz .LBB0_575

.LBB0_575:
	s_nop 1
	v_cvt_pk_bf16_f32 v88, v100, v101
	s_nop 1
	v_cvt_pk_bf16_f32 v89, v102, v103
	s_nop 1
	v_cvt_pk_bf16_f32 v90, v96, v97
	s_nop 1
	v_cvt_pk_bf16_f32 v91, v98, v99
	global_store_dwordx4 v[104:105], v[88:91], off
	s_nop 1
	v_mov_b64_e32 v[88:89], v[216:217]
	v_lshl_add_u64 v[96:97], v[104:105], 0, s[72:73]
	s_and_b64 vcc, exec, s[82:83]
	v_cvt_f32_ubyte3_e32 v91, v88
	v_cvt_f32_ubyte2_e32 v90, v88
	v_cvt_f32_ubyte1_e32 v93, v88
	v_cvt_f32_ubyte0_e32 v92, v88
	v_cvt_f32_ubyte3_e32 v95, v89
	v_cvt_f32_ubyte2_e32 v94, v89
	v_cvt_f32_ubyte1_e32 v99, v89
	v_cvt_f32_ubyte0_e32 v98, v89
	v_pk_mul_f32 v[88:89], v[92:93], s[74:75] op_sel_hi:[1,0]
	v_pk_mul_f32 v[90:91], v[90:91], s[74:75] op_sel_hi:[1,0]
	v_pk_mul_f32 v[92:93], v[98:99], s[74:75] op_sel_hi:[1,0]
	v_pk_mul_f32 v[94:95], v[94:95], s[74:75] op_sel_hi:[1,0]
	v_pk_mul_f32 v[86:87], v[86:87], v[90:91]
	v_pk_mul_f32 v[84:85], v[84:85], v[88:89]
	v_pk_mul_f32 v[82:83], v[82:83], v[94:95]
	v_pk_mul_f32 v[80:81], v[80:81], v[92:93]
	s_cbranch_vccz .LBB0_607
	v_mov_b64_e32 v[88:89], v[194:195]
	v_mov_b64_e32 v[90:91], v[196:197]
	v_lshlrev_b32_e32 v92, 16, v88
	v_and_b32_e32 v93, 0xffff0000, v88
	v_lshlrev_b32_e32 v88, 16, v89
	v_and_b32_e32 v89, 0xffff0000, v89
	v_lshlrev_b32_e32 v98, 16, v90
	v_and_b32_e32 v99, 0xffff0000, v90
	v_lshlrev_b32_e32 v90, 16, v91
	v_and_b32_e32 v91, 0xffff0000, v91
	v_pk_add_f32 v[94:95], v[86:87], v[88:89]
	v_pk_add_f32 v[92:93], v[84:85], v[92:93]
	v_pk_add_f32 v[90:91], v[82:83], v[90:91]
	v_pk_add_f32 v[88:89], v[80:81], v[98:99]
	s_cbranch_execnz .LBB0_578

.LBB0_578:
	s_nop 1
	v_cvt_pk_bf16_f32 v80, v92, v93
	s_nop 1
	v_cvt_pk_bf16_f32 v81, v94, v95
	s_nop 1
	v_cvt_pk_bf16_f32 v82, v88, v89
	s_nop 1
	v_cvt_pk_bf16_f32 v83, v90, v91
	global_store_dwordx4 v[96:97], v[80:83], off
	v_mov_b64_e32 v[84:85], s[84:85]
	s_and_b64 vcc, exec, s[82:83]
	v_add_u32_e32 v80, 0xb0, v176
	v_ashrrev_i32_e32 v81, 31, v80
	v_lshlrev_b64 v[82:83], 12, v[80:81]
	v_mad_i64_i32 v[80:81], s[26:27], v80, s13, v[84:85]
	v_lshl_add_u64 v[90:91], v[80:81], 0, v[174:175]
	v_mov_b64_e32 v[80:81], v[218:219]
	v_cvt_f32_ubyte1_e32 v87, v80
	v_cvt_f32_ubyte0_e32 v86, v80
	v_cvt_f32_ubyte3_e32 v85, v80
	v_cvt_f32_ubyte2_e32 v84, v80
	v_pk_mul_f32 v[86:87], v[86:87], s[74:75] op_sel_hi:[1,0]
	v_pk_mul_f32 v[84:85], v[84:85], s[74:75] op_sel_hi:[1,0]
	v_pk_mul_f32 v[76:77], v[76:77], v[86:87]
	v_cvt_f32_ubyte1_e32 v87, v81
	v_cvt_f32_ubyte0_e32 v86, v81
	v_pk_mul_f32 v[78:79], v[78:79], v[84:85]
	v_cvt_f32_ubyte3_e32 v85, v81
	v_cvt_f32_ubyte2_e32 v84, v81
	v_pk_mul_f32 v[80:81], v[86:87], s[74:75] op_sel_hi:[1,0]
	v_pk_mul_f32 v[84:85], v[84:85], s[74:75] op_sel_hi:[1,0]
	v_pk_mul_f32 v[72:73], v[72:73], v[80:81]
	v_lshl_add_u64 v[80:81], s[2:3], 0, v[82:83]
	v_pk_mul_f32 v[74:75], v[74:75], v[84:85]
	v_lshl_add_u64 v[88:89], v[174:175], 1, v[80:81]
	s_cbranch_vccz .LBB0_608
	v_mov_b64_e32 v[80:81], v[198:199]
	v_mov_b64_e32 v[82:83], v[200:201]
	v_lshlrev_b32_e32 v84, 16, v80
	v_and_b32_e32 v85, 0xffff0000, v80
	v_lshlrev_b32_e32 v80, 16, v81
	v_and_b32_e32 v81, 0xffff0000, v81
	v_lshlrev_b32_e32 v92, 16, v82
	v_and_b32_e32 v93, 0xffff0000, v82
	v_lshlrev_b32_e32 v82, 16, v83
	v_and_b32_e32 v83, 0xffff0000, v83
	v_pk_add_f32 v[86:87], v[78:79], v[80:81]
	v_pk_add_f32 v[84:85], v[76:77], v[84:85]
	v_pk_add_f32 v[82:83], v[74:75], v[82:83]
	v_pk_add_f32 v[80:81], v[72:73], v[92:93]
	s_cbranch_execnz .LBB0_581

.LBB0_581:
	s_nop 1
	v_cvt_pk_bf16_f32 v72, v84, v85
	s_nop 1
	v_cvt_pk_bf16_f32 v73, v86, v87
	s_nop 1
	v_cvt_pk_bf16_f32 v74, v80, v81
	s_nop 1
	v_cvt_pk_bf16_f32 v75, v82, v83
	global_store_dwordx4 v[88:89], v[72:75], off
	s_nop 1
	v_mov_b64_e32 v[72:73], v[220:221]
	v_lshl_add_u64 v[80:81], v[88:89], 0, s[72:73]
	s_and_b64 vcc, exec, s[82:83]
	v_cvt_f32_ubyte3_e32 v75, v72
	v_cvt_f32_ubyte2_e32 v74, v72
	v_cvt_f32_ubyte1_e32 v77, v72
	v_cvt_f32_ubyte0_e32 v76, v72
	v_cvt_f32_ubyte3_e32 v79, v73
	v_cvt_f32_ubyte2_e32 v78, v73
	v_cvt_f32_ubyte1_e32 v83, v73
	v_cvt_f32_ubyte0_e32 v82, v73
	v_pk_mul_f32 v[72:73], v[76:77], s[74:75] op_sel_hi:[1,0]
	v_pk_mul_f32 v[74:75], v[74:75], s[74:75] op_sel_hi:[1,0]
	v_pk_mul_f32 v[76:77], v[82:83], s[74:75] op_sel_hi:[1,0]
	v_pk_mul_f32 v[78:79], v[78:79], s[74:75] op_sel_hi:[1,0]
	v_pk_mul_f32 v[70:71], v[70:71], v[74:75]
	v_pk_mul_f32 v[68:69], v[68:69], v[72:73]
	v_pk_mul_f32 v[66:67], v[66:67], v[78:79]
	v_pk_mul_f32 v[64:65], v[64:65], v[76:77]
	s_cbranch_vccz .LBB0_609
	v_mov_b64_e32 v[72:73], v[202:203]
	v_mov_b64_e32 v[74:75], v[204:205]
	v_lshlrev_b32_e32 v76, 16, v72
	v_and_b32_e32 v77, 0xffff0000, v72
	v_lshlrev_b32_e32 v72, 16, v73
	v_and_b32_e32 v73, 0xffff0000, v73
	v_lshlrev_b32_e32 v82, 16, v74
	v_and_b32_e32 v83, 0xffff0000, v74
	v_lshlrev_b32_e32 v74, 16, v75
	v_and_b32_e32 v75, 0xffff0000, v75
	v_pk_add_f32 v[78:79], v[70:71], v[72:73]
	v_pk_add_f32 v[76:77], v[68:69], v[76:77]
	v_pk_add_f32 v[74:75], v[66:67], v[74:75]
	v_pk_add_f32 v[72:73], v[64:65], v[82:83]
	s_cbranch_execnz .LBB0_584

.LBB0_1470:
	s_lshl_b32 s51, s84, 8
	v_or_b32_e32 v174, s51, v186
	s_mov_b64 s[8:9], -1
	s_cmp_gt_i32 s4, -1
	v_ashrrev_i32_e32 v175, 31, v174
	s_cbranch_scc1 .LBB0_1520
	v_lshl_add_u32 v176, s85, 8, v152
	v_mov_b64_e32 v[128:129], s[46:47]
	v_mad_i64_i32 v[128:129], s[8:9], v176, s17, v[128:129]
	v_lshl_add_u64 v[178:179], v[128:129], 0, v[174:175]
	v_mov_b64_e32 v[206:207], s[46:47]
	v_mul_lo_u32 v222, v176, s17
	v_mov_b32_e32 v223, 0
	v_lshl_add_u64 v[206:207], v[206:207], 0, v[222:223]
	v_lshl_add_u64 v[206:207], v[206:207], 0, v[174:175]
	v_lshlrev_b32_e32 v208, 12, v176
	v_mov_b32_e32 v209, 0
	v_lshl_add_u64 v[208:209], s[6:7], 0, v[208:209]
	v_lshl_add_u64 v[208:209], v[174:175], 1, v[208:209]
	v_mov_b64_e32 v[210:211], v[206:207]
	v_mov_b64_e32 v[212:213], v[208:209]
	global_load_dwordx2 v[214:215], v[210:211], off
	global_load_dwordx2 v[216:217], v[210:211], off offset:128
	global_load_dwordx4 v[190:193], v[212:213], off
	global_load_dwordx4 v[194:197], v[212:213], off offset:256
	v_mov_b32_e32 v222, 0x18000
	v_mov_b32_e32 v223, 0
	v_lshl_add_u64 v[210:211], v[210:211], 0, v[222:223]
	v_mov_b32_e32 v222, 0x10000
	v_mov_b32_e32 v223, 0
	v_lshl_add_u64 v[212:213], v[212:213], 0, v[222:223]
	global_load_dwordx2 v[218:219], v[210:211], off
	global_load_dwordx2 v[220:221], v[210:211], off offset:128
	global_load_dwordx4 v[198:201], v[212:213], off
	global_load_dwordx4 v[202:205], v[212:213], off offset:256
	s_waitcnt vmcnt(0)
	v_mov_b64_e32 v[128:129], v[214:215]
	v_ashrrev_i32_e32 v177, 31, v176
	v_lshlrev_b64 v[130:131], 12, v[176:177]
	v_lshl_add_u64 v[130:131], s[6:7], 0, v[130:131]
	v_lshl_add_u64 v[180:181], v[174:175], 1, v[130:131]
	s_and_b64 vcc, exec, s[44:45]
	v_cvt_f32_ubyte3_e32 v131, v128
	v_cvt_f32_ubyte2_e32 v130, v128
	v_cvt_f32_ubyte1_e32 v133, v128
	v_cvt_f32_ubyte0_e32 v132, v128
	v_cvt_f32_ubyte3_e32 v135, v129
	v_cvt_f32_ubyte2_e32 v134, v129
	v_cvt_f32_ubyte1_e32 v137, v129
	v_cvt_f32_ubyte0_e32 v136, v129
	v_pk_mul_f32 v[128:129], v[132:133], s[36:37] op_sel_hi:[1,0]
	v_pk_mul_f32 v[130:131], v[130:131], s[36:37] op_sel_hi:[1,0]
	v_pk_mul_f32 v[132:133], v[136:137], s[36:37] op_sel_hi:[1,0]
	v_pk_mul_f32 v[134:135], v[134:135], s[36:37] op_sel_hi:[1,0]
	v_pk_mul_f32 v[130:131], v[62:63], v[130:131]
	v_pk_mul_f32 v[128:129], v[60:61], v[128:129]
	v_pk_mul_f32 v[134:135], v[58:59], v[134:135]
	v_pk_mul_f32 v[132:133], v[56:57], v[132:133]
	s_cbranch_vccz .LBB0_1529
	v_mov_b64_e32 v[136:137], v[190:191]
	v_mov_b64_e32 v[138:139], v[192:193]
	v_lshlrev_b32_e32 v140, 16, v136
	v_and_b32_e32 v141, 0xffff0000, v136
	v_lshlrev_b32_e32 v136, 16, v137
	v_and_b32_e32 v137, 0xffff0000, v137
	v_lshlrev_b32_e32 v188, 16, v138
	v_and_b32_e32 v189, 0xffff0000, v138
	v_lshlrev_b32_e32 v138, 16, v139
	v_and_b32_e32 v139, 0xffff0000, v139
	v_pk_add_f32 v[142:143], v[130:131], v[136:137]
	v_pk_add_f32 v[140:141], v[128:129], v[140:141]
	v_pk_add_f32 v[138:139], v[134:135], v[138:139]
	v_pk_add_f32 v[136:137], v[132:133], v[188:189]
	s_cbranch_execnz .LBB0_1474

.LBB0_1474:
	s_nop 1
	v_cvt_pk_bf16_f32 v128, v140, v141
	s_nop 1
	v_cvt_pk_bf16_f32 v129, v142, v143
	s_nop 1
	v_cvt_pk_bf16_f32 v130, v136, v137
	s_nop 1
	v_cvt_pk_bf16_f32 v131, v138, v139
	global_store_dwordx4 v[180:181], v[128:131], off
	s_nop 1
	v_mov_b64_e32 v[128:129], v[216:217]
	v_lshl_add_u64 v[178:179], v[180:181], 0, s[34:35]
	s_and_b64 vcc, exec, s[44:45]
	v_cvt_f32_ubyte3_e32 v131, v128
	v_cvt_f32_ubyte2_e32 v130, v128
	v_cvt_f32_ubyte1_e32 v133, v128
	v_cvt_f32_ubyte0_e32 v132, v128
	v_cvt_f32_ubyte3_e32 v135, v129
	v_cvt_f32_ubyte2_e32 v134, v129
	v_cvt_f32_ubyte1_e32 v137, v129
	v_cvt_f32_ubyte0_e32 v136, v129
	v_pk_mul_f32 v[128:129], v[132:133], s[36:37] op_sel_hi:[1,0]
	v_pk_mul_f32 v[130:131], v[130:131], s[36:37] op_sel_hi:[1,0]
	v_pk_mul_f32 v[132:133], v[136:137], s[36:37] op_sel_hi:[1,0]
	v_pk_mul_f32 v[134:135], v[134:135], s[36:37] op_sel_hi:[1,0]
	v_pk_mul_f32 v[130:131], v[54:55], v[130:131]
	v_pk_mul_f32 v[128:129], v[52:53], v[128:129]
	v_pk_mul_f32 v[134:135], v[50:51], v[134:135]
	v_pk_mul_f32 v[132:133], v[48:49], v[132:133]
	s_cbranch_vccz .LBB0_1530
	v_mov_b64_e32 v[136:137], v[194:195]
	v_mov_b64_e32 v[138:139], v[196:197]
	v_lshlrev_b32_e32 v140, 16, v136
	v_and_b32_e32 v141, 0xffff0000, v136
	v_lshlrev_b32_e32 v136, 16, v137
	v_and_b32_e32 v137, 0xffff0000, v137
	v_lshlrev_b32_e32 v180, 16, v138
	v_and_b32_e32 v181, 0xffff0000, v138
	v_lshlrev_b32_e32 v138, 16, v139
	v_and_b32_e32 v139, 0xffff0000, v139
	v_pk_add_f32 v[142:143], v[130:131], v[136:137]
	v_pk_add_f32 v[140:141], v[128:129], v[140:141]
	v_pk_add_f32 v[138:139], v[134:135], v[138:139]
	v_pk_add_f32 v[136:137], v[132:133], v[180:181]
	s_cbranch_execnz .LBB0_1477

.LBB0_1477:
	s_nop 1
	v_cvt_pk_bf16_f32 v128, v140, v141
	s_nop 1
	v_cvt_pk_bf16_f32 v129, v142, v143
	s_nop 1
	v_cvt_pk_bf16_f32 v130, v136, v137
	s_nop 1
	v_cvt_pk_bf16_f32 v131, v138, v139
	global_store_dwordx4 v[178:179], v[128:131], off
	s_and_b64 vcc, exec, s[44:45]
	s_nop 0
	v_or_b32_e32 v128, 16, v176
	v_mov_b64_e32 v[130:131], s[46:47]
	v_mad_i64_i32 v[130:131], s[8:9], v128, s17, v[130:131]
	v_lshl_add_u64 v[178:179], v[130:131], 0, v[174:175]
	v_mov_b64_e32 v[130:131], v[218:219]
	v_ashrrev_i32_e32 v129, 31, v128
	v_lshlrev_b64 v[128:129], 12, v[128:129]
	v_lshl_add_u64 v[128:129], s[6:7], 0, v[128:129]
	v_lshl_add_u64 v[180:181], v[174:175], 1, v[128:129]
	v_cvt_f32_ubyte3_e32 v129, v130
	v_cvt_f32_ubyte2_e32 v128, v130
	v_cvt_f32_ubyte1_e32 v133, v130
	v_cvt_f32_ubyte0_e32 v132, v130
	v_cvt_f32_ubyte3_e32 v135, v131
	v_cvt_f32_ubyte2_e32 v134, v131
	v_cvt_f32_ubyte1_e32 v137, v131
	v_cvt_f32_ubyte0_e32 v136, v131
	v_pk_mul_f32 v[132:133], v[132:133], s[36:37] op_sel_hi:[1,0]
	v_pk_mul_f32 v[128:129], v[128:129], s[36:37] op_sel_hi:[1,0]
	v_pk_mul_f32 v[136:137], v[136:137], s[36:37] op_sel_hi:[1,0]
	v_pk_mul_f32 v[134:135], v[134:135], s[36:37] op_sel_hi:[1,0]
	v_pk_mul_f32 v[130:131], v[46:47], v[128:129]
	v_pk_mul_f32 v[128:129], v[44:45], v[132:133]
	v_pk_mul_f32 v[134:135], v[42:43], v[134:135]
	v_pk_mul_f32 v[132:133], v[40:41], v[136:137]
	s_cbranch_vccz .LBB0_1531
	v_mov_b64_e32 v[136:137], v[198:199]
	v_mov_b64_e32 v[138:139], v[200:201]
	v_lshlrev_b32_e32 v140, 16, v136
	v_and_b32_e32 v141, 0xffff0000, v136
	v_lshlrev_b32_e32 v136, 16, v137
	v_and_b32_e32 v137, 0xffff0000, v137
	v_lshlrev_b32_e32 v188, 16, v138
	v_and_b32_e32 v189, 0xffff0000, v138
	v_lshlrev_b32_e32 v138, 16, v139
	v_and_b32_e32 v139, 0xffff0000, v139
	v_pk_add_f32 v[142:143], v[130:131], v[136:137]
	v_pk_add_f32 v[140:141], v[128:129], v[140:141]
	v_pk_add_f32 v[138:139], v[134:135], v[138:139]
	v_pk_add_f32 v[136:137], v[132:133], v[188:189]
	s_cbranch_execnz .LBB0_1480

.LBB0_1480:
	s_nop 1
	v_cvt_pk_bf16_f32 v128, v140, v141
	s_nop 1
	v_cvt_pk_bf16_f32 v129, v142, v143
	s_nop 1
	v_cvt_pk_bf16_f32 v130, v136, v137
	s_nop 1
	v_cvt_pk_bf16_f32 v131, v138, v139
	global_store_dwordx4 v[180:181], v[128:131], off
	s_nop 1
	v_mov_b64_e32 v[128:129], v[220:221]
	v_lshl_add_u64 v[178:179], v[180:181], 0, s[34:35]
	s_and_b64 vcc, exec, s[44:45]
	v_cvt_f32_ubyte3_e32 v131, v128
	v_cvt_f32_ubyte2_e32 v130, v128
	v_cvt_f32_ubyte1_e32 v133, v128
	v_cvt_f32_ubyte0_e32 v132, v128
	v_cvt_f32_ubyte3_e32 v135, v129
	v_cvt_f32_ubyte2_e32 v134, v129
	v_cvt_f32_ubyte1_e32 v137, v129
	v_cvt_f32_ubyte0_e32 v136, v129
	v_pk_mul_f32 v[128:129], v[132:133], s[36:37] op_sel_hi:[1,0]
	v_pk_mul_f32 v[130:131], v[130:131], s[36:37] op_sel_hi:[1,0]
	v_pk_mul_f32 v[132:133], v[136:137], s[36:37] op_sel_hi:[1,0]
	v_pk_mul_f32 v[134:135], v[134:135], s[36:37] op_sel_hi:[1,0]
	v_pk_mul_f32 v[130:131], v[38:39], v[130:131]
	v_pk_mul_f32 v[128:129], v[36:37], v[128:129]
	v_pk_mul_f32 v[134:135], v[34:35], v[134:135]
	v_pk_mul_f32 v[132:133], v[32:33], v[132:133]
	s_cbranch_vccz .LBB0_1532
	v_mov_b64_e32 v[136:137], v[202:203]
	v_mov_b64_e32 v[138:139], v[204:205]
	v_lshlrev_b32_e32 v140, 16, v136
	v_and_b32_e32 v141, 0xffff0000, v136
	v_lshlrev_b32_e32 v136, 16, v137
	v_and_b32_e32 v137, 0xffff0000, v137
	v_lshlrev_b32_e32 v180, 16, v138
	v_and_b32_e32 v181, 0xffff0000, v138
	v_lshlrev_b32_e32 v138, 16, v139
	v_and_b32_e32 v139, 0xffff0000, v139
	v_pk_add_f32 v[142:143], v[130:131], v[136:137]
	v_pk_add_f32 v[140:141], v[128:129], v[140:141]
	v_pk_add_f32 v[138:139], v[134:135], v[138:139]
	v_pk_add_f32 v[136:137], v[132:133], v[180:181]
	s_cbranch_execnz .LBB0_1483

.LBB0_1483:
	s_nop 1
	v_cvt_pk_bf16_f32 v128, v140, v141
	s_nop 1
	v_cvt_pk_bf16_f32 v129, v142, v143
	s_nop 1
	v_cvt_pk_bf16_f32 v130, v136, v137
	s_nop 1
	v_cvt_pk_bf16_f32 v131, v138, v139
	global_store_dwordx4 v[178:179], v[128:131], off
	s_and_b64 vcc, exec, s[44:45]
	s_nop 0
	v_or_b32_e32 v128, 32, v176
	v_mov_b64_e32 v[130:131], s[46:47]
	v_mad_i64_i32 v[130:131], s[8:9], v128, s17, v[130:131]
	v_lshl_add_u64 v[178:179], v[130:131], 0, v[174:175]
	v_mov_b64_e32 v[210:211], v[206:207]
	v_mov_b64_e32 v[212:213], v[208:209]
	v_mov_b32_e32 v222, 0x30000
	v_mov_b32_e32 v223, 0
	v_lshl_add_u64 v[210:211], v[210:211], 0, v[222:223]
	v_mov_b32_e32 v222, 0x20000
	v_mov_b32_e32 v223, 0
	v_lshl_add_u64 v[212:213], v[212:213], 0, v[222:223]
	global_load_dwordx2 v[214:215], v[210:211], off
	global_load_dwordx2 v[216:217], v[210:211], off offset:128
	global_load_dwordx4 v[190:193], v[212:213], off
	global_load_dwordx4 v[194:197], v[212:213], off offset:256
	v_mov_b32_e32 v222, 0x18000
	v_mov_b32_e32 v223, 0
	v_lshl_add_u64 v[210:211], v[210:211], 0, v[222:223]
	v_mov_b32_e32 v222, 0x10000
	v_mov_b32_e32 v223, 0
	v_lshl_add_u64 v[212:213], v[212:213], 0, v[222:223]
	global_load_dwordx2 v[218:219], v[210:211], off
	global_load_dwordx2 v[220:221], v[210:211], off offset:128
	global_load_dwordx4 v[198:201], v[212:213], off
	global_load_dwordx4 v[202:205], v[212:213], off offset:256
	s_waitcnt vmcnt(0)
	v_mov_b64_e32 v[130:131], v[214:215]
	v_ashrrev_i32_e32 v129, 31, v128
	v_lshlrev_b64 v[128:129], 12, v[128:129]
	v_lshl_add_u64 v[128:129], s[6:7], 0, v[128:129]
	v_lshl_add_u64 v[180:181], v[174:175], 1, v[128:129]
	v_cvt_f32_ubyte3_e32 v129, v130
	v_cvt_f32_ubyte2_e32 v128, v130
	v_cvt_f32_ubyte1_e32 v133, v130
	v_cvt_f32_ubyte0_e32 v132, v130
	v_cvt_f32_ubyte3_e32 v135, v131
	v_cvt_f32_ubyte2_e32 v134, v131
	v_cvt_f32_ubyte1_e32 v137, v131
	v_cvt_f32_ubyte0_e32 v136, v131
	v_pk_mul_f32 v[132:133], v[132:133], s[36:37] op_sel_hi:[1,0]
	v_pk_mul_f32 v[128:129], v[128:129], s[36:37] op_sel_hi:[1,0]
	v_pk_mul_f32 v[136:137], v[136:137], s[36:37] op_sel_hi:[1,0]
	v_pk_mul_f32 v[134:135], v[134:135], s[36:37] op_sel_hi:[1,0]
	v_pk_mul_f32 v[130:131], v[30:31], v[128:129]
	v_pk_mul_f32 v[128:129], v[28:29], v[132:133]
	v_pk_mul_f32 v[134:135], v[26:27], v[134:135]
	v_pk_mul_f32 v[132:133], v[24:25], v[136:137]
	s_cbranch_vccz .LBB0_1533
	v_mov_b64_e32 v[136:137], v[190:191]
	v_mov_b64_e32 v[138:139], v[192:193]
	v_lshlrev_b32_e32 v140, 16, v136
	v_and_b32_e32 v141, 0xffff0000, v136
	v_lshlrev_b32_e32 v136, 16, v137
	v_and_b32_e32 v137, 0xffff0000, v137
	v_lshlrev_b32_e32 v188, 16, v138
	v_and_b32_e32 v189, 0xffff0000, v138
	v_lshlrev_b32_e32 v138, 16, v139
	v_and_b32_e32 v139, 0xffff0000, v139
	v_pk_add_f32 v[142:143], v[130:131], v[136:137]
	v_pk_add_f32 v[140:141], v[128:129], v[140:141]
	v_pk_add_f32 v[138:139], v[134:135], v[138:139]
	v_pk_add_f32 v[136:137], v[132:133], v[188:189]
	s_cbranch_execnz .LBB0_1486

.LBB0_1486:
	s_nop 1
	v_cvt_pk_bf16_f32 v128, v140, v141
	s_nop 1
	v_cvt_pk_bf16_f32 v129, v142, v143
	s_nop 1
	v_cvt_pk_bf16_f32 v130, v136, v137
	s_nop 1
	v_cvt_pk_bf16_f32 v131, v138, v139
	global_store_dwordx4 v[180:181], v[128:131], off
	s_nop 1
	v_mov_b64_e32 v[128:129], v[216:217]
	v_lshl_add_u64 v[178:179], v[180:181], 0, s[34:35]
	s_and_b64 vcc, exec, s[44:45]
	v_cvt_f32_ubyte3_e32 v131, v128
	v_cvt_f32_ubyte2_e32 v130, v128
	v_cvt_f32_ubyte1_e32 v133, v128
	v_cvt_f32_ubyte0_e32 v132, v128
	v_cvt_f32_ubyte3_e32 v135, v129
	v_cvt_f32_ubyte2_e32 v134, v129
	v_cvt_f32_ubyte1_e32 v137, v129
	v_cvt_f32_ubyte0_e32 v136, v129
	v_pk_mul_f32 v[128:129], v[132:133], s[36:37] op_sel_hi:[1,0]
	v_pk_mul_f32 v[130:131], v[130:131], s[36:37] op_sel_hi:[1,0]
	v_pk_mul_f32 v[132:133], v[136:137], s[36:37] op_sel_hi:[1,0]
	v_pk_mul_f32 v[134:135], v[134:135], s[36:37] op_sel_hi:[1,0]
	v_pk_mul_f32 v[130:131], v[22:23], v[130:131]
	v_pk_mul_f32 v[128:129], v[20:21], v[128:129]
	v_pk_mul_f32 v[134:135], v[18:19], v[134:135]
	v_pk_mul_f32 v[132:133], v[16:17], v[132:133]
	s_cbranch_vccz .LBB0_1534
	v_mov_b64_e32 v[136:137], v[194:195]
	v_mov_b64_e32 v[138:139], v[196:197]
	v_lshlrev_b32_e32 v140, 16, v136
	v_and_b32_e32 v141, 0xffff0000, v136
	v_lshlrev_b32_e32 v136, 16, v137
	v_and_b32_e32 v137, 0xffff0000, v137
	v_lshlrev_b32_e32 v180, 16, v138
	v_and_b32_e32 v181, 0xffff0000, v138
	v_lshlrev_b32_e32 v138, 16, v139
	v_and_b32_e32 v139, 0xffff0000, v139
	v_pk_add_f32 v[142:143], v[130:131], v[136:137]
	v_pk_add_f32 v[140:141], v[128:129], v[140:141]
	v_pk_add_f32 v[138:139], v[134:135], v[138:139]
	v_pk_add_f32 v[136:137], v[132:133], v[180:181]
	s_cbranch_execnz .LBB0_1489

.LBB0_1489:
	s_nop 1
	v_cvt_pk_bf16_f32 v128, v140, v141
	s_nop 1
	v_cvt_pk_bf16_f32 v129, v142, v143
	s_nop 1
	v_cvt_pk_bf16_f32 v130, v136, v137
	s_nop 1
	v_cvt_pk_bf16_f32 v131, v138, v139
	global_store_dwordx4 v[178:179], v[128:131], off
	s_and_b64 vcc, exec, s[44:45]
	s_nop 0
	v_or_b32_e32 v128, 48, v176
	v_mov_b64_e32 v[130:131], s[46:47]
	v_mad_i64_i32 v[130:131], s[8:9], v128, s17, v[130:131]
	v_lshl_add_u64 v[178:179], v[130:131], 0, v[174:175]
	v_mov_b64_e32 v[130:131], v[218:219]
	v_ashrrev_i32_e32 v129, 31, v128
	v_lshlrev_b64 v[128:129], 12, v[128:129]
	v_lshl_add_u64 v[128:129], s[6:7], 0, v[128:129]
	v_lshl_add_u64 v[180:181], v[174:175], 1, v[128:129]
	v_cvt_f32_ubyte3_e32 v129, v130
	v_cvt_f32_ubyte2_e32 v128, v130
	v_cvt_f32_ubyte1_e32 v133, v130
	v_cvt_f32_ubyte0_e32 v132, v130
	v_cvt_f32_ubyte3_e32 v135, v131
	v_cvt_f32_ubyte2_e32 v134, v131
	v_cvt_f32_ubyte1_e32 v137, v131
	v_cvt_f32_ubyte0_e32 v136, v131
	v_pk_mul_f32 v[132:133], v[132:133], s[36:37] op_sel_hi:[1,0]
	v_pk_mul_f32 v[128:129], v[128:129], s[36:37] op_sel_hi:[1,0]
	v_pk_mul_f32 v[136:137], v[136:137], s[36:37] op_sel_hi:[1,0]
	v_pk_mul_f32 v[134:135], v[134:135], s[36:37] op_sel_hi:[1,0]
	v_pk_mul_f32 v[130:131], v[14:15], v[128:129]
	v_pk_mul_f32 v[128:129], v[12:13], v[132:133]
	v_pk_mul_f32 v[134:135], v[10:11], v[134:135]
	v_pk_mul_f32 v[132:133], v[8:9], v[136:137]
	s_cbranch_vccz .LBB0_1535
	v_mov_b64_e32 v[136:137], v[198:199]
	v_mov_b64_e32 v[138:139], v[200:201]
	v_lshlrev_b32_e32 v140, 16, v136
	v_and_b32_e32 v141, 0xffff0000, v136
	v_lshlrev_b32_e32 v136, 16, v137
	v_and_b32_e32 v137, 0xffff0000, v137
	v_lshlrev_b32_e32 v188, 16, v138
	v_and_b32_e32 v189, 0xffff0000, v138
	v_lshlrev_b32_e32 v138, 16, v139
	v_and_b32_e32 v139, 0xffff0000, v139
	v_pk_add_f32 v[142:143], v[130:131], v[136:137]
	v_pk_add_f32 v[140:141], v[128:129], v[140:141]
	v_pk_add_f32 v[138:139], v[134:135], v[138:139]
	v_pk_add_f32 v[136:137], v[132:133], v[188:189]
	s_cbranch_execnz .LBB0_1492

.LBB0_1492:
	s_nop 1
	v_cvt_pk_bf16_f32 v128, v140, v141
	s_nop 1
	v_cvt_pk_bf16_f32 v129, v142, v143
	s_nop 1
	v_cvt_pk_bf16_f32 v130, v136, v137
	s_nop 1
	v_cvt_pk_bf16_f32 v131, v138, v139
	global_store_dwordx4 v[180:181], v[128:131], off
	s_nop 1
	v_mov_b64_e32 v[128:129], v[220:221]
	v_lshl_add_u64 v[178:179], v[180:181], 0, s[34:35]
	s_and_b64 vcc, exec, s[44:45]
	v_cvt_f32_ubyte3_e32 v131, v128
	v_cvt_f32_ubyte2_e32 v130, v128
	v_cvt_f32_ubyte1_e32 v133, v128
	v_cvt_f32_ubyte0_e32 v132, v128
	v_cvt_f32_ubyte3_e32 v135, v129
	v_cvt_f32_ubyte2_e32 v134, v129
	v_cvt_f32_ubyte1_e32 v137, v129
	v_cvt_f32_ubyte0_e32 v136, v129
	v_pk_mul_f32 v[128:129], v[132:133], s[36:37] op_sel_hi:[1,0]
	v_pk_mul_f32 v[130:131], v[130:131], s[36:37] op_sel_hi:[1,0]
	v_pk_mul_f32 v[132:133], v[136:137], s[36:37] op_sel_hi:[1,0]
	v_pk_mul_f32 v[134:135], v[134:135], s[36:37] op_sel_hi:[1,0]
	v_pk_mul_f32 v[130:131], v[6:7], v[130:131]
	v_pk_mul_f32 v[128:129], v[4:5], v[128:129]
	v_pk_mul_f32 v[134:135], v[2:3], v[134:135]
	v_pk_mul_f32 v[132:133], v[0:1], v[132:133]
	s_cbranch_vccz .LBB0_1536
	v_mov_b64_e32 v[136:137], v[202:203]
	v_mov_b64_e32 v[138:139], v[204:205]
	v_lshlrev_b32_e32 v140, 16, v136
	v_and_b32_e32 v141, 0xffff0000, v136
	v_lshlrev_b32_e32 v136, 16, v137
	v_and_b32_e32 v137, 0xffff0000, v137
	v_lshlrev_b32_e32 v180, 16, v138
	v_and_b32_e32 v181, 0xffff0000, v138
	v_lshlrev_b32_e32 v138, 16, v139
	v_and_b32_e32 v139, 0xffff0000, v139
	v_pk_add_f32 v[142:143], v[130:131], v[136:137]
	v_pk_add_f32 v[140:141], v[128:129], v[140:141]
	v_pk_add_f32 v[138:139], v[134:135], v[138:139]
	v_pk_add_f32 v[136:137], v[132:133], v[180:181]
	s_cbranch_execnz .LBB0_1495

.LBB0_1495:
	s_nop 1
	v_cvt_pk_bf16_f32 v128, v140, v141
	s_nop 1
	v_cvt_pk_bf16_f32 v129, v142, v143
	s_nop 1
	v_cvt_pk_bf16_f32 v130, v136, v137
	s_nop 1
	v_cvt_pk_bf16_f32 v131, v138, v139
	global_store_dwordx4 v[178:179], v[128:131], off
	v_mov_b64_e32 v[132:133], s[46:47]
	s_and_b64 vcc, exec, s[44:45]
	v_add_u32_e32 v128, 0x80, v176
	v_ashrrev_i32_e32 v129, 31, v128
	v_lshlrev_b64 v[130:131], 12, v[128:129]
	v_mad_i64_i32 v[128:129], s[8:9], v128, s17, v[132:133]
	v_lshl_add_u64 v[138:139], v[128:129], 0, v[174:175]
	v_mov_b64_e32 v[210:211], v[206:207]
	v_mov_b64_e32 v[212:213], v[208:209]
	v_mov_b32_e32 v222, 0xc0000
	v_mov_b32_e32 v223, 0
	v_lshl_add_u64 v[210:211], v[210:211], 0, v[222:223]
	v_mov_b32_e32 v222, 0x80000
	v_mov_b32_e32 v223, 0
	v_lshl_add_u64 v[212:213], v[212:213], 0, v[222:223]
	global_load_dwordx2 v[214:215], v[210:211], off
	global_load_dwordx2 v[216:217], v[210:211], off offset:128
	global_load_dwordx4 v[190:193], v[212:213], off
	global_load_dwordx4 v[194:197], v[212:213], off offset:256
	v_mov_b32_e32 v222, 0x18000
	v_mov_b32_e32 v223, 0
	v_lshl_add_u64 v[210:211], v[210:211], 0, v[222:223]
	v_mov_b32_e32 v222, 0x10000
	v_mov_b32_e32 v223, 0
	v_lshl_add_u64 v[212:213], v[212:213], 0, v[222:223]
	global_load_dwordx2 v[218:219], v[210:211], off
	global_load_dwordx2 v[220:221], v[210:211], off offset:128
	global_load_dwordx4 v[198:201], v[212:213], off
	global_load_dwordx4 v[202:205], v[212:213], off offset:256
	s_waitcnt vmcnt(0)
	v_mov_b64_e32 v[128:129], v[214:215]
	v_cvt_f32_ubyte1_e32 v135, v128
	v_cvt_f32_ubyte0_e32 v134, v128
	v_cvt_f32_ubyte3_e32 v133, v128
	v_cvt_f32_ubyte2_e32 v132, v128
	v_pk_mul_f32 v[134:135], v[134:135], s[36:37] op_sel_hi:[1,0]
	v_pk_mul_f32 v[132:133], v[132:133], s[36:37] op_sel_hi:[1,0]
	v_pk_mul_f32 v[124:125], v[124:125], v[134:135]
	v_cvt_f32_ubyte1_e32 v135, v129
	v_cvt_f32_ubyte0_e32 v134, v129
	v_pk_mul_f32 v[126:127], v[126:127], v[132:133]
	v_cvt_f32_ubyte3_e32 v133, v129
	v_cvt_f32_ubyte2_e32 v132, v129
	v_pk_mul_f32 v[128:129], v[134:135], s[36:37] op_sel_hi:[1,0]
	v_pk_mul_f32 v[132:133], v[132:133], s[36:37] op_sel_hi:[1,0]
	v_pk_mul_f32 v[120:121], v[120:121], v[128:129]
	v_lshl_add_u64 v[128:129], s[6:7], 0, v[130:131]
	v_pk_mul_f32 v[122:123], v[122:123], v[132:133]
	v_lshl_add_u64 v[136:137], v[174:175], 1, v[128:129]
	s_cbranch_vccz .LBB0_1537
	v_mov_b64_e32 v[128:129], v[190:191]
	v_mov_b64_e32 v[130:131], v[192:193]
	v_lshlrev_b32_e32 v132, 16, v128
	v_and_b32_e32 v133, 0xffff0000, v128
	v_lshlrev_b32_e32 v128, 16, v129
	v_and_b32_e32 v129, 0xffff0000, v129
	v_lshlrev_b32_e32 v140, 16, v130
	v_and_b32_e32 v141, 0xffff0000, v130
	v_lshlrev_b32_e32 v130, 16, v131
	v_and_b32_e32 v131, 0xffff0000, v131
	v_pk_add_f32 v[134:135], v[126:127], v[128:129]
	v_pk_add_f32 v[132:133], v[124:125], v[132:133]
	v_pk_add_f32 v[130:131], v[122:123], v[130:131]
	v_pk_add_f32 v[128:129], v[120:121], v[140:141]
	s_cbranch_execnz .LBB0_1498

.LBB0_1498:
	s_nop 1
	v_cvt_pk_bf16_f32 v120, v132, v133
	s_nop 1
	v_cvt_pk_bf16_f32 v121, v134, v135
	s_nop 1
	v_cvt_pk_bf16_f32 v122, v128, v129
	s_nop 1
	v_cvt_pk_bf16_f32 v123, v130, v131
	global_store_dwordx4 v[136:137], v[120:123], off
	s_nop 1
	v_mov_b64_e32 v[120:121], v[216:217]
	v_lshl_add_u64 v[128:129], v[136:137], 0, s[34:35]
	s_and_b64 vcc, exec, s[44:45]
	v_cvt_f32_ubyte3_e32 v123, v120
	v_cvt_f32_ubyte2_e32 v122, v120
	v_cvt_f32_ubyte1_e32 v125, v120
	v_cvt_f32_ubyte0_e32 v124, v120
	v_cvt_f32_ubyte3_e32 v127, v121
	v_cvt_f32_ubyte2_e32 v126, v121
	v_cvt_f32_ubyte1_e32 v131, v121
	v_cvt_f32_ubyte0_e32 v130, v121
	v_pk_mul_f32 v[120:121], v[124:125], s[36:37] op_sel_hi:[1,0]
	v_pk_mul_f32 v[122:123], v[122:123], s[36:37] op_sel_hi:[1,0]
	v_pk_mul_f32 v[124:125], v[130:131], s[36:37] op_sel_hi:[1,0]
	v_pk_mul_f32 v[126:127], v[126:127], s[36:37] op_sel_hi:[1,0]
	v_pk_mul_f32 v[118:119], v[118:119], v[122:123]
	v_pk_mul_f32 v[116:117], v[116:117], v[120:121]
	v_pk_mul_f32 v[114:115], v[114:115], v[126:127]
	v_pk_mul_f32 v[112:113], v[112:113], v[124:125]
	s_cbranch_vccz .LBB0_1538
	v_mov_b64_e32 v[120:121], v[194:195]
	v_mov_b64_e32 v[122:123], v[196:197]
	v_lshlrev_b32_e32 v124, 16, v120
	v_and_b32_e32 v125, 0xffff0000, v120
	v_lshlrev_b32_e32 v120, 16, v121
	v_and_b32_e32 v121, 0xffff0000, v121
	v_lshlrev_b32_e32 v130, 16, v122
	v_and_b32_e32 v131, 0xffff0000, v122
	v_lshlrev_b32_e32 v122, 16, v123
	v_and_b32_e32 v123, 0xffff0000, v123
	v_pk_add_f32 v[126:127], v[118:119], v[120:121]
	v_pk_add_f32 v[124:125], v[116:117], v[124:125]
	v_pk_add_f32 v[122:123], v[114:115], v[122:123]
	v_pk_add_f32 v[120:121], v[112:113], v[130:131]
	s_cbranch_execnz .LBB0_1501

.LBB0_1501:
	s_nop 1
	v_cvt_pk_bf16_f32 v112, v124, v125
	s_nop 1
	v_cvt_pk_bf16_f32 v113, v126, v127
	s_nop 1
	v_cvt_pk_bf16_f32 v114, v120, v121
	s_nop 1
	v_cvt_pk_bf16_f32 v115, v122, v123
	global_store_dwordx4 v[128:129], v[112:115], off
	v_mov_b64_e32 v[116:117], s[46:47]
	s_and_b64 vcc, exec, s[44:45]
	v_add_u32_e32 v112, 0x90, v176
	v_ashrrev_i32_e32 v113, 31, v112
	v_lshlrev_b64 v[114:115], 12, v[112:113]
	v_mad_i64_i32 v[112:113], s[8:9], v112, s17, v[116:117]
	v_lshl_add_u64 v[122:123], v[112:113], 0, v[174:175]
	v_mov_b64_e32 v[112:113], v[218:219]
	v_cvt_f32_ubyte1_e32 v119, v112
	v_cvt_f32_ubyte0_e32 v118, v112
	v_cvt_f32_ubyte3_e32 v117, v112
	v_cvt_f32_ubyte2_e32 v116, v112
	v_pk_mul_f32 v[118:119], v[118:119], s[36:37] op_sel_hi:[1,0]
	v_pk_mul_f32 v[116:117], v[116:117], s[36:37] op_sel_hi:[1,0]
	v_pk_mul_f32 v[108:109], v[108:109], v[118:119]
	v_cvt_f32_ubyte1_e32 v119, v113
	v_cvt_f32_ubyte0_e32 v118, v113
	v_pk_mul_f32 v[110:111], v[110:111], v[116:117]
	v_cvt_f32_ubyte3_e32 v117, v113
	v_cvt_f32_ubyte2_e32 v116, v113
	v_pk_mul_f32 v[112:113], v[118:119], s[36:37] op_sel_hi:[1,0]
	v_pk_mul_f32 v[116:117], v[116:117], s[36:37] op_sel_hi:[1,0]
	v_pk_mul_f32 v[104:105], v[104:105], v[112:113]
	v_lshl_add_u64 v[112:113], s[6:7], 0, v[114:115]
	v_pk_mul_f32 v[106:107], v[106:107], v[116:117]
	v_lshl_add_u64 v[120:121], v[174:175], 1, v[112:113]
	s_cbranch_vccz .LBB0_1539
	v_mov_b64_e32 v[112:113], v[198:199]
	v_mov_b64_e32 v[114:115], v[200:201]
	v_lshlrev_b32_e32 v116, 16, v112
	v_and_b32_e32 v117, 0xffff0000, v112
	v_lshlrev_b32_e32 v112, 16, v113
	v_and_b32_e32 v113, 0xffff0000, v113
	v_lshlrev_b32_e32 v124, 16, v114
	v_and_b32_e32 v125, 0xffff0000, v114
	v_lshlrev_b32_e32 v114, 16, v115
	v_and_b32_e32 v115, 0xffff0000, v115
	v_pk_add_f32 v[118:119], v[110:111], v[112:113]
	v_pk_add_f32 v[116:117], v[108:109], v[116:117]
	v_pk_add_f32 v[114:115], v[106:107], v[114:115]
	v_pk_add_f32 v[112:113], v[104:105], v[124:125]
	s_cbranch_execnz .LBB0_1504

.LBB0_1504:
	s_nop 1
	v_cvt_pk_bf16_f32 v104, v116, v117
	s_nop 1
	v_cvt_pk_bf16_f32 v105, v118, v119
	s_nop 1
	v_cvt_pk_bf16_f32 v106, v112, v113
	s_nop 1
	v_cvt_pk_bf16_f32 v107, v114, v115
	global_store_dwordx4 v[120:121], v[104:107], off
	s_nop 1
	v_mov_b64_e32 v[104:105], v[220:221]
	v_lshl_add_u64 v[112:113], v[120:121], 0, s[34:35]
	s_and_b64 vcc, exec, s[44:45]
	v_cvt_f32_ubyte3_e32 v107, v104
	v_cvt_f32_ubyte2_e32 v106, v104
	v_cvt_f32_ubyte1_e32 v109, v104
	v_cvt_f32_ubyte0_e32 v108, v104
	v_cvt_f32_ubyte3_e32 v111, v105
	v_cvt_f32_ubyte2_e32 v110, v105
	v_cvt_f32_ubyte1_e32 v115, v105
	v_cvt_f32_ubyte0_e32 v114, v105
	v_pk_mul_f32 v[104:105], v[108:109], s[36:37] op_sel_hi:[1,0]
	v_pk_mul_f32 v[106:107], v[106:107], s[36:37] op_sel_hi:[1,0]
	v_pk_mul_f32 v[108:109], v[114:115], s[36:37] op_sel_hi:[1,0]
	v_pk_mul_f32 v[110:111], v[110:111], s[36:37] op_sel_hi:[1,0]
	v_pk_mul_f32 v[102:103], v[102:103], v[106:107]
	v_pk_mul_f32 v[100:101], v[100:101], v[104:105]
	v_pk_mul_f32 v[98:99], v[98:99], v[110:111]
	v_pk_mul_f32 v[96:97], v[96:97], v[108:109]
	s_cbranch_vccz .LBB0_1540
	v_mov_b64_e32 v[104:105], v[202:203]
	v_mov_b64_e32 v[106:107], v[204:205]
	v_lshlrev_b32_e32 v108, 16, v104
	v_and_b32_e32 v109, 0xffff0000, v104
	v_lshlrev_b32_e32 v104, 16, v105
	v_and_b32_e32 v105, 0xffff0000, v105
	v_lshlrev_b32_e32 v114, 16, v106
	v_and_b32_e32 v115, 0xffff0000, v106
	v_lshlrev_b32_e32 v106, 16, v107
	v_and_b32_e32 v107, 0xffff0000, v107
	v_pk_add_f32 v[110:111], v[102:103], v[104:105]
	v_pk_add_f32 v[108:109], v[100:101], v[108:109]
	v_pk_add_f32 v[106:107], v[98:99], v[106:107]
	v_pk_add_f32 v[104:105], v[96:97], v[114:115]
	s_cbranch_execnz .LBB0_1507

.LBB0_1507:
	s_nop 1
	v_cvt_pk_bf16_f32 v96, v108, v109
	s_nop 1
	v_cvt_pk_bf16_f32 v97, v110, v111
	s_nop 1
	v_cvt_pk_bf16_f32 v98, v104, v105
	s_nop 1
	v_cvt_pk_bf16_f32 v99, v106, v107
	global_store_dwordx4 v[112:113], v[96:99], off
	v_mov_b64_e32 v[100:101], s[46:47]
	s_and_b64 vcc, exec, s[44:45]
	v_add_u32_e32 v96, 0xa0, v176
	v_ashrrev_i32_e32 v97, 31, v96
	v_lshlrev_b64 v[98:99], 12, v[96:97]
	v_mad_i64_i32 v[96:97], s[8:9], v96, s17, v[100:101]
	v_lshl_add_u64 v[106:107], v[96:97], 0, v[174:175]
	v_mov_b64_e32 v[210:211], v[206:207]
	v_mov_b64_e32 v[212:213], v[208:209]
	v_mov_b32_e32 v222, 0xf0000
	v_mov_b32_e32 v223, 0
	v_lshl_add_u64 v[210:211], v[210:211], 0, v[222:223]
	v_mov_b32_e32 v222, 0xa0000
	v_mov_b32_e32 v223, 0
	v_lshl_add_u64 v[212:213], v[212:213], 0, v[222:223]
	global_load_dwordx2 v[214:215], v[210:211], off
	global_load_dwordx2 v[216:217], v[210:211], off offset:128
	global_load_dwordx4 v[190:193], v[212:213], off
	global_load_dwordx4 v[194:197], v[212:213], off offset:256
	v_mov_b32_e32 v222, 0x18000
	v_mov_b32_e32 v223, 0
	v_lshl_add_u64 v[210:211], v[210:211], 0, v[222:223]
	v_mov_b32_e32 v222, 0x10000
	v_mov_b32_e32 v223, 0
	v_lshl_add_u64 v[212:213], v[212:213], 0, v[222:223]
	global_load_dwordx2 v[218:219], v[210:211], off
	global_load_dwordx2 v[220:221], v[210:211], off offset:128
	global_load_dwordx4 v[198:201], v[212:213], off
	global_load_dwordx4 v[202:205], v[212:213], off offset:256
	s_waitcnt vmcnt(0)
	v_mov_b64_e32 v[96:97], v[214:215]
	v_cvt_f32_ubyte1_e32 v103, v96
	v_cvt_f32_ubyte0_e32 v102, v96
	v_cvt_f32_ubyte3_e32 v101, v96
	v_cvt_f32_ubyte2_e32 v100, v96
	v_pk_mul_f32 v[102:103], v[102:103], s[36:37] op_sel_hi:[1,0]
	v_pk_mul_f32 v[100:101], v[100:101], s[36:37] op_sel_hi:[1,0]
	v_pk_mul_f32 v[92:93], v[92:93], v[102:103]
	v_cvt_f32_ubyte1_e32 v103, v97
	v_cvt_f32_ubyte0_e32 v102, v97
	v_pk_mul_f32 v[94:95], v[94:95], v[100:101]
	v_cvt_f32_ubyte3_e32 v101, v97
	v_cvt_f32_ubyte2_e32 v100, v97
	v_pk_mul_f32 v[96:97], v[102:103], s[36:37] op_sel_hi:[1,0]
	v_pk_mul_f32 v[100:101], v[100:101], s[36:37] op_sel_hi:[1,0]
	v_pk_mul_f32 v[88:89], v[88:89], v[96:97]
	v_lshl_add_u64 v[96:97], s[6:7], 0, v[98:99]
	v_pk_mul_f32 v[90:91], v[90:91], v[100:101]
	v_lshl_add_u64 v[104:105], v[174:175], 1, v[96:97]
	s_cbranch_vccz .LBB0_1541
	v_mov_b64_e32 v[96:97], v[190:191]
	v_mov_b64_e32 v[98:99], v[192:193]
	v_lshlrev_b32_e32 v100, 16, v96
	v_and_b32_e32 v101, 0xffff0000, v96
	v_lshlrev_b32_e32 v96, 16, v97
	v_and_b32_e32 v97, 0xffff0000, v97
	v_lshlrev_b32_e32 v108, 16, v98
	v_and_b32_e32 v109, 0xffff0000, v98
	v_lshlrev_b32_e32 v98, 16, v99
	v_and_b32_e32 v99, 0xffff0000, v99
	v_pk_add_f32 v[102:103], v[94:95], v[96:97]
	v_pk_add_f32 v[100:101], v[92:93], v[100:101]
	v_pk_add_f32 v[98:99], v[90:91], v[98:99]
	v_pk_add_f32 v[96:97], v[88:89], v[108:109]
	s_cbranch_execnz .LBB0_1510

.LBB0_1510:
	s_nop 1
	v_cvt_pk_bf16_f32 v88, v100, v101
	s_nop 1
	v_cvt_pk_bf16_f32 v89, v102, v103
	s_nop 1
	v_cvt_pk_bf16_f32 v90, v96, v97
	s_nop 1
	v_cvt_pk_bf16_f32 v91, v98, v99
	global_store_dwordx4 v[104:105], v[88:91], off
	s_nop 1
	v_mov_b64_e32 v[88:89], v[216:217]
	v_lshl_add_u64 v[96:97], v[104:105], 0, s[34:35]
	s_and_b64 vcc, exec, s[44:45]
	v_cvt_f32_ubyte3_e32 v91, v88
	v_cvt_f32_ubyte2_e32 v90, v88
	v_cvt_f32_ubyte1_e32 v93, v88
	v_cvt_f32_ubyte0_e32 v92, v88
	v_cvt_f32_ubyte3_e32 v95, v89
	v_cvt_f32_ubyte2_e32 v94, v89
	v_cvt_f32_ubyte1_e32 v99, v89
	v_cvt_f32_ubyte0_e32 v98, v89
	v_pk_mul_f32 v[88:89], v[92:93], s[36:37] op_sel_hi:[1,0]
	v_pk_mul_f32 v[90:91], v[90:91], s[36:37] op_sel_hi:[1,0]
	v_pk_mul_f32 v[92:93], v[98:99], s[36:37] op_sel_hi:[1,0]
	v_pk_mul_f32 v[94:95], v[94:95], s[36:37] op_sel_hi:[1,0]
	v_pk_mul_f32 v[86:87], v[86:87], v[90:91]
	v_pk_mul_f32 v[84:85], v[84:85], v[88:89]
	v_pk_mul_f32 v[82:83], v[82:83], v[94:95]
	v_pk_mul_f32 v[80:81], v[80:81], v[92:93]
	s_cbranch_vccz .LBB0_1542
	v_mov_b64_e32 v[88:89], v[194:195]
	v_mov_b64_e32 v[90:91], v[196:197]
	v_lshlrev_b32_e32 v92, 16, v88
	v_and_b32_e32 v93, 0xffff0000, v88
	v_lshlrev_b32_e32 v88, 16, v89
	v_and_b32_e32 v89, 0xffff0000, v89
	v_lshlrev_b32_e32 v98, 16, v90
	v_and_b32_e32 v99, 0xffff0000, v90
	v_lshlrev_b32_e32 v90, 16, v91
	v_and_b32_e32 v91, 0xffff0000, v91
	v_pk_add_f32 v[94:95], v[86:87], v[88:89]
	v_pk_add_f32 v[92:93], v[84:85], v[92:93]
	v_pk_add_f32 v[90:91], v[82:83], v[90:91]
	v_pk_add_f32 v[88:89], v[80:81], v[98:99]
	s_cbranch_execnz .LBB0_1513

.LBB0_1513:
	s_nop 1
	v_cvt_pk_bf16_f32 v80, v92, v93
	s_nop 1
	v_cvt_pk_bf16_f32 v81, v94, v95
	s_nop 1
	v_cvt_pk_bf16_f32 v82, v88, v89
	s_nop 1
	v_cvt_pk_bf16_f32 v83, v90, v91
	global_store_dwordx4 v[96:97], v[80:83], off
	v_mov_b64_e32 v[84:85], s[46:47]
	s_and_b64 vcc, exec, s[44:45]
	v_add_u32_e32 v80, 0xb0, v176
	v_ashrrev_i32_e32 v81, 31, v80
	v_lshlrev_b64 v[82:83], 12, v[80:81]
	v_mad_i64_i32 v[80:81], s[8:9], v80, s17, v[84:85]
	v_lshl_add_u64 v[90:91], v[80:81], 0, v[174:175]
	v_mov_b64_e32 v[80:81], v[218:219]
	v_cvt_f32_ubyte1_e32 v87, v80
	v_cvt_f32_ubyte0_e32 v86, v80
	v_cvt_f32_ubyte3_e32 v85, v80
	v_cvt_f32_ubyte2_e32 v84, v80
	v_pk_mul_f32 v[86:87], v[86:87], s[36:37] op_sel_hi:[1,0]
	v_pk_mul_f32 v[84:85], v[84:85], s[36:37] op_sel_hi:[1,0]
	v_pk_mul_f32 v[76:77], v[76:77], v[86:87]
	v_cvt_f32_ubyte1_e32 v87, v81
	v_cvt_f32_ubyte0_e32 v86, v81
	v_pk_mul_f32 v[78:79], v[78:79], v[84:85]
	v_cvt_f32_ubyte3_e32 v85, v81
	v_cvt_f32_ubyte2_e32 v84, v81
	v_pk_mul_f32 v[80:81], v[86:87], s[36:37] op_sel_hi:[1,0]
	v_pk_mul_f32 v[84:85], v[84:85], s[36:37] op_sel_hi:[1,0]
	v_pk_mul_f32 v[72:73], v[72:73], v[80:81]
	v_lshl_add_u64 v[80:81], s[6:7], 0, v[82:83]
	v_pk_mul_f32 v[74:75], v[74:75], v[84:85]
	v_lshl_add_u64 v[88:89], v[174:175], 1, v[80:81]
	s_cbranch_vccz .LBB0_1543
	v_mov_b64_e32 v[80:81], v[198:199]
	v_mov_b64_e32 v[82:83], v[200:201]
	v_lshlrev_b32_e32 v84, 16, v80
	v_and_b32_e32 v85, 0xffff0000, v80
	v_lshlrev_b32_e32 v80, 16, v81
	v_and_b32_e32 v81, 0xffff0000, v81
	v_lshlrev_b32_e32 v92, 16, v82
	v_and_b32_e32 v93, 0xffff0000, v82
	v_lshlrev_b32_e32 v82, 16, v83
	v_and_b32_e32 v83, 0xffff0000, v83
	v_pk_add_f32 v[86:87], v[78:79], v[80:81]
	v_pk_add_f32 v[84:85], v[76:77], v[84:85]
	v_pk_add_f32 v[82:83], v[74:75], v[82:83]
	v_pk_add_f32 v[80:81], v[72:73], v[92:93]
	s_cbranch_execnz .LBB0_1516

.LBB0_1516:
	s_nop 1
	v_cvt_pk_bf16_f32 v72, v84, v85
	s_nop 1
	v_cvt_pk_bf16_f32 v73, v86, v87
	s_nop 1
	v_cvt_pk_bf16_f32 v74, v80, v81
	s_nop 1
	v_cvt_pk_bf16_f32 v75, v82, v83
	global_store_dwordx4 v[88:89], v[72:75], off
	s_nop 1
	v_mov_b64_e32 v[72:73], v[220:221]
	v_lshl_add_u64 v[80:81], v[88:89], 0, s[34:35]
	s_and_b64 vcc, exec, s[44:45]
	v_cvt_f32_ubyte3_e32 v75, v72
	v_cvt_f32_ubyte2_e32 v74, v72
	v_cvt_f32_ubyte1_e32 v77, v72
	v_cvt_f32_ubyte0_e32 v76, v72
	v_cvt_f32_ubyte3_e32 v79, v73
	v_cvt_f32_ubyte2_e32 v78, v73
	v_cvt_f32_ubyte1_e32 v83, v73
	v_cvt_f32_ubyte0_e32 v82, v73
	v_pk_mul_f32 v[72:73], v[76:77], s[36:37] op_sel_hi:[1,0]
	v_pk_mul_f32 v[74:75], v[74:75], s[36:37] op_sel_hi:[1,0]
	v_pk_mul_f32 v[76:77], v[82:83], s[36:37] op_sel_hi:[1,0]
	v_pk_mul_f32 v[78:79], v[78:79], s[36:37] op_sel_hi:[1,0]
	v_pk_mul_f32 v[70:71], v[70:71], v[74:75]
	v_pk_mul_f32 v[68:69], v[68:69], v[72:73]
	v_pk_mul_f32 v[66:67], v[66:67], v[78:79]
	v_pk_mul_f32 v[64:65], v[64:65], v[76:77]
	s_cbranch_vccz .LBB0_1544
	v_mov_b64_e32 v[72:73], v[202:203]
	v_mov_b64_e32 v[74:75], v[204:205]
	v_lshlrev_b32_e32 v76, 16, v72
	v_and_b32_e32 v77, 0xffff0000, v72
	v_lshlrev_b32_e32 v72, 16, v73
	v_and_b32_e32 v73, 0xffff0000, v73
	v_lshlrev_b32_e32 v82, 16, v74
	v_and_b32_e32 v83, 0xffff0000, v74
	v_lshlrev_b32_e32 v74, 16, v75
	v_and_b32_e32 v75, 0xffff0000, v75
	v_pk_add_f32 v[78:79], v[70:71], v[72:73]
	v_pk_add_f32 v[76:77], v[68:69], v[76:77]
	v_pk_add_f32 v[74:75], v[66:67], v[74:75]
	v_pk_add_f32 v[72:73], v[64:65], v[82:83]
	s_cbranch_execnz .LBB0_1519

.LBB0_1944:
	s_and_b64 vcc, exec, s[36:37]
	s_cbranch_vccz .LBB0_1950
	v_readlane_b32 s36, v254, 56
	v_readlane_b32 s37, v254, 57
	s_lshl_b64 s[36:37], s[36:37], 20
	s_add_u32 s36, s6, s36
	s_addc_u32 s37, s7, s37
	v_lshl_add_u64 v[0:1], s[36:37], 0, v[138:139]
	v_lshlrev_b64 v[2:3], 2, v[150:151]
	v_lshl_add_u64 v[0:1], v[0:1], 0, v[2:3]
	global_store_dwordx4 v[0:1], v[76:79], off
	global_store_dwordx4 v[0:1], v[72:75], off offset:16
	global_store_dwordx4 v[0:1], v[44:47], off offset:512
	global_store_dwordx4 v[0:1], v[40:43], off offset:528
	v_lshl_add_u64 v[0:1], s[36:37], 0, v[140:141]
	v_lshl_add_u64 v[0:1], v[0:1], 0, v[2:3]
	global_store_dwordx4 v[0:1], v[68:71], off
	global_store_dwordx4 v[0:1], v[64:67], off offset:16
	global_store_dwordx4 v[0:1], v[28:31], off offset:512
	global_store_dwordx4 v[0:1], v[24:27], off offset:528
	v_lshl_add_u64 v[0:1], s[36:37], 0, v[142:143]
	v_lshl_add_u64 v[0:1], v[0:1], 0, v[2:3]
	global_store_dwordx4 v[0:1], v[56:59], off
	global_store_dwordx4 v[0:1], v[48:51], off offset:16
	global_store_dwordx4 v[0:1], v[20:23], off offset:512
	global_store_dwordx4 v[0:1], v[16:19], off offset:528
	v_lshl_add_u64 v[0:1], s[36:37], 0, v[144:145]
	v_lshl_add_u64 v[0:1], v[0:1], 0, v[2:3]
	global_store_dwordx4 v[0:1], v[36:39], off
	global_store_dwordx4 v[0:1], v[32:35], off offset:16
	global_store_dwordx4 v[0:1], v[8:11], off offset:512
	global_store_dwordx4 v[0:1], v[4:7], off offset:528
	s_waitcnt vmcnt(0)
	s_waitcnt vmcnt(0)
	s_barrier
	s_and_saveexec_b64 s[36:37], s[18:19]
	s_cbranch_execz .LBB0_1947
	s_lshl_b32 s40, s89, 6
	s_ashr_i32 s41, s40, 31
	s_lshl_b64 s[40:41], s[40:41], 2
	s_add_u32 s40, s51, s40
	s_addc_u32 s41, s52, s41
	buffer_wbl2 sc1
	s_waitcnt vmcnt(0)
	v_mov_b64_e32 v[0:1], s[40:41]
	flat_atomic_add v0, v[0:1], v156 sc0
	s_waitcnt vmcnt(0) lgkmcnt(0)
	ds_write_b32 v131, v0
	v_mov_b64_e32 v[2:3], s[40:41]

.Lsl_go_dn21:
.LBB0_1947:
	s_or_b64 exec, exec, s[36:37]
	s_waitcnt lgkmcnt(0)
	s_barrier
	ds_read_b32 v0, v131
	s_waitcnt lgkmcnt(0)
	v_readfirstlane_b32 s36, v0
	v_mov_b32_e32 v48, v183
	buffer_inv sc1
	s_waitcnt vmcnt(0)
	s_lshl_b32 s36, s36, 9
	v_lshlrev_b32_e32 v0, 2, v48
	v_and_b32_e32 v0, 0xfc, v0
	v_or_b32_e32 v36, s38, v0
	v_ashrrev_i32_e32 v37, 31, v36
	v_lshl_add_u64 v[38:39], v[36:37], 2, s[6:7]
	s_cmpk_lt_i32 s36, 0x2000
	s_cbranch_scc0 .LBB0_1950
.LBB0_1949:
	s_nop 0
	v_add_u32_e32 v0, s36, v48
	v_ashrrev_i32_e32 v2, 6, v0
	v_ashrrev_i32_e32 v3, 31, v2
	v_lshlrev_b64 v[4:5], 11, v[2:3]
	v_lshl_add_u64 v[4:5], v[4:5], 0, v[36:37]
	v_lshl_add_u64 v[34:35], v[4:5], 0, s[26:27]
	v_lshl_add_u64 v[4:5], v[34:35], 1, s[4:5]
	global_load_dwordx2 v[4:5], v[4:5], off
	v_lshlrev_b64 v[2:3], 13, v[2:3]
	v_lshl_add_u64 v[62:63], v[38:39], 0, v[2:3]
	v_add_co_u32_e32 v6, vcc, s61, v62
	v_add_u32_e32 v1, 0x200, v0
	s_nop 0
	v_addc_co_u32_e32 v7, vcc, 0, v63, vcc
	v_add_co_u32_e32 v10, vcc, s62, v62
	global_load_dwordx4 v[6:9], v[6:7], off
	s_nop 0
	v_addc_co_u32_e32 v11, vcc, 0, v63, vcc
	v_add_co_u32_e32 v14, vcc, s63, v62
	global_load_dwordx4 v[10:13], v[10:11], off
	s_nop 0
	v_addc_co_u32_e32 v15, vcc, 0, v63, vcc
	v_add_co_u32_e32 v18, vcc, s64, v62
	global_load_dwordx4 v[14:17], v[14:15], off
	s_nop 0
	v_addc_co_u32_e32 v19, vcc, 0, v63, vcc
	v_add_co_u32_e32 v22, vcc, s65, v62
	global_load_dwordx4 v[18:21], v[18:19], off
	s_nop 0
	v_addc_co_u32_e32 v23, vcc, 0, v63, vcc
	v_add_co_u32_e32 v26, vcc, s66, v62
	global_load_dwordx4 v[22:25], v[22:23], off
	s_nop 0
	v_addc_co_u32_e32 v27, vcc, 0, v63, vcc
	v_add_co_u32_e32 v30, vcc, s67, v62
	global_load_dwordx4 v[26:29], v[26:27], off
	s_nop 0
	v_addc_co_u32_e32 v31, vcc, 0, v63, vcc
	v_add_co_u32_e32 v40, vcc, s70, v62
	global_load_dwordx4 v[30:33], v[30:31], off
	s_nop 0
	v_addc_co_u32_e32 v41, vcc, 0, v63, vcc
	v_add_co_u32_e32 v44, vcc, s71, v62
	global_load_dwordx4 v[40:43], v[40:41], off
	s_nop 0
	v_addc_co_u32_e32 v45, vcc, 0, v63, vcc
	v_add_co_u32_e32 v50, vcc, s72, v62
	global_load_dwordx4 v[44:47], v[44:45], off
	s_nop 0
	v_addc_co_u32_e32 v51, vcc, 0, v63, vcc
	v_add_co_u32_e32 v54, vcc, s73, v62
	global_load_dwordx4 v[50:53], v[50:51], off
	s_nop 0
	v_addc_co_u32_e32 v55, vcc, 0, v63, vcc
	global_load_dwordx4 v[54:57], v[54:55], off
	s_addk_i32 s36, 0x800
	s_cmpk_eq_i32 s36, 0x2000
	s_waitcnt vmcnt(11)
	v_lshlrev_b32_e32 v58, 16, v4
	v_and_b32_e32 v59, 0xffff0000, v4
	v_lshlrev_b32_e32 v60, 16, v5
	v_and_b32_e32 v61, 0xffff0000, v5
	global_load_dwordx4 v[2:5], v[62:63], off
	s_waitcnt vmcnt(0)
	v_pk_add_f32 v[2:3], v[2:3], v[58:59]
	v_pk_add_f32 v[4:5], v[4:5], v[60:61]
	v_pk_add_f32 v[2:3], v[6:7], v[2:3]
	v_pk_add_f32 v[4:5], v[8:9], v[4:5]
	v_pk_add_f32 v[2:3], v[10:11], v[2:3]
	v_pk_add_f32 v[4:5], v[12:13], v[4:5]
	v_pk_add_f32 v[2:3], v[14:15], v[2:3]
	v_pk_add_f32 v[4:5], v[16:17], v[4:5]
	v_pk_add_f32 v[2:3], v[18:19], v[2:3]
	v_pk_add_f32 v[4:5], v[20:21], v[4:5]
	v_pk_add_f32 v[2:3], v[22:23], v[2:3]
	v_pk_add_f32 v[4:5], v[24:25], v[4:5]
	v_pk_add_f32 v[2:3], v[26:27], v[2:3]
	v_pk_add_f32 v[4:5], v[28:29], v[4:5]
	v_pk_add_f32 v[2:3], v[30:31], v[2:3]
	v_pk_add_f32 v[4:5], v[32:33], v[4:5]
	v_pk_add_f32 v[2:3], v[40:41], v[2:3]
	v_pk_add_f32 v[4:5], v[42:43], v[4:5]
	v_pk_add_f32 v[2:3], v[44:45], v[2:3]
	v_pk_add_f32 v[4:5], v[46:47], v[4:5]
	v_pk_add_f32 v[2:3], v[50:51], v[2:3]
	v_pk_add_f32 v[4:5], v[52:53], v[4:5]
	v_pk_add_f32 v[52:53], v[54:55], v[2:3]
	v_add_co_u32_e32 v2, vcc, s74, v62
	v_pk_add_f32 v[50:51], v[56:57], v[4:5]
	s_nop 0
	v_addc_co_u32_e32 v3, vcc, 0, v63, vcc
	v_add_co_u32_e32 v6, vcc, s75, v62
	global_load_dwordx4 v[2:5], v[2:3], off
	s_nop 0
	v_addc_co_u32_e32 v7, vcc, 0, v63, vcc
	v_add_co_u32_e32 v10, vcc, s76, v62
	global_load_dwordx4 v[6:9], v[6:7], off
	s_nop 0
	v_addc_co_u32_e32 v11, vcc, 0, v63, vcc
	v_add_co_u32_e32 v14, vcc, s77, v62
	global_load_dwordx4 v[10:13], v[10:11], off
	s_nop 0
	v_addc_co_u32_e32 v15, vcc, 0, v63, vcc
	v_add_co_u32_e32 v18, vcc, s78, v62
	global_load_dwordx4 v[14:17], v[14:15], off
	s_nop 0
	v_addc_co_u32_e32 v19, vcc, 0, v63, vcc
	v_add_co_u32_e32 v22, vcc, s79, v62
	global_load_dwordx4 v[18:21], v[18:19], off
	s_nop 0
	v_addc_co_u32_e32 v23, vcc, 0, v63, vcc
	v_add_co_u32_e32 v26, vcc, s80, v62
	global_load_dwordx4 v[22:25], v[22:23], off
	s_nop 0
	v_addc_co_u32_e32 v27, vcc, 0, v63, vcc
	v_add_co_u32_e32 v30, vcc, s81, v62
	global_load_dwordx4 v[26:29], v[26:27], off
	s_nop 0
	v_addc_co_u32_e32 v31, vcc, 0, v63, vcc
	v_add_co_u32_e32 v40, vcc, s82, v62
	global_load_dwordx4 v[30:33], v[30:31], off
	s_nop 0
	v_addc_co_u32_e32 v41, vcc, 0, v63, vcc
	v_add_co_u32_e32 v44, vcc, s83, v62
	global_load_dwordx4 v[40:43], v[40:41], off
	s_nop 0
	v_addc_co_u32_e32 v45, vcc, 0, v63, vcc
	global_load_dwordx4 v[44:47], v[44:45], off
	s_waitcnt vmcnt(9)
	v_pk_add_f32 v[4:5], v[4:5], v[50:51]
	v_pk_add_f32 v[2:3], v[2:3], v[52:53]
	s_waitcnt vmcnt(8)
	v_pk_add_f32 v[4:5], v[8:9], v[4:5]
	v_pk_add_f32 v[2:3], v[6:7], v[2:3]
	v_lshl_add_u64 v[6:7], v[34:35], 2, s[68:69]
	s_waitcnt vmcnt(7)
	v_pk_add_f32 v[4:5], v[12:13], v[4:5]
	v_pk_add_f32 v[2:3], v[10:11], v[2:3]
	s_waitcnt vmcnt(6)
	v_pk_add_f32 v[4:5], v[16:17], v[4:5]
	v_pk_add_f32 v[2:3], v[14:15], v[2:3]
	s_waitcnt vmcnt(5)
	v_pk_add_f32 v[4:5], v[20:21], v[4:5]
	v_pk_add_f32 v[2:3], v[18:19], v[2:3]
	s_waitcnt vmcnt(4)
	v_pk_add_f32 v[4:5], v[24:25], v[4:5]
	v_pk_add_f32 v[2:3], v[22:23], v[2:3]
	s_waitcnt vmcnt(3)
	v_pk_add_f32 v[4:5], v[28:29], v[4:5]
	v_pk_add_f32 v[2:3], v[26:27], v[2:3]
	s_waitcnt vmcnt(2)
	v_pk_add_f32 v[4:5], v[32:33], v[4:5]
	v_pk_add_f32 v[2:3], v[30:31], v[2:3]
	s_waitcnt vmcnt(1)
	v_pk_add_f32 v[4:5], v[42:43], v[4:5]
	v_pk_add_f32 v[2:3], v[40:41], v[2:3]
	s_waitcnt vmcnt(0)
	v_pk_add_f32 v[4:5], v[46:47], v[4:5]
	v_pk_add_f32 v[2:3], v[44:45], v[2:3]
	global_store_dwordx4 v[6:7], v[2:5], off
	s_addk_i32 s36, 0x2400
	s_cmpk_lt_i32 s36, 0x2000
	s_cbranch_scc1 .LBB0_1949
	s_branch .LBB0_1950
	s_nop 1
	v_ashrrev_i32_e32 v2, 6, v1
	v_ashrrev_i32_e32 v3, 31, v2
	v_lshlrev_b64 v[4:5], 11, v[2:3]
	v_lshl_add_u64 v[4:5], v[4:5], 0, v[36:37]
	v_lshl_add_u64 v[34:35], v[4:5], 0, s[26:27]
	v_lshl_add_u64 v[4:5], v[34:35], 1, s[4:5]
	global_load_dwordx2 v[4:5], v[4:5], off
	v_lshlrev_b64 v[2:3], 13, v[2:3]
	v_lshl_add_u64 v[62:63], v[38:39], 0, v[2:3]
	v_add_co_u32_e32 v6, vcc, s61, v62
	v_add_u32_e32 v1, 0x400, v0
	s_nop 0
	v_addc_co_u32_e32 v7, vcc, 0, v63, vcc
	v_add_co_u32_e32 v10, vcc, s62, v62
	global_load_dwordx4 v[6:9], v[6:7], off
	s_nop 0
	v_addc_co_u32_e32 v11, vcc, 0, v63, vcc
	v_add_co_u32_e32 v14, vcc, s63, v62
	global_load_dwordx4 v[10:13], v[10:11], off
	s_nop 0
	v_addc_co_u32_e32 v15, vcc, 0, v63, vcc
	v_add_co_u32_e32 v18, vcc, s64, v62
	global_load_dwordx4 v[14:17], v[14:15], off
	s_nop 0
	v_addc_co_u32_e32 v19, vcc, 0, v63, vcc
	v_add_co_u32_e32 v22, vcc, s65, v62
	global_load_dwordx4 v[18:21], v[18:19], off
	s_nop 0
	v_addc_co_u32_e32 v23, vcc, 0, v63, vcc
	v_add_co_u32_e32 v26, vcc, s66, v62
	global_load_dwordx4 v[22:25], v[22:23], off
	s_nop 0
	v_addc_co_u32_e32 v27, vcc, 0, v63, vcc
	v_add_co_u32_e32 v30, vcc, s67, v62
	global_load_dwordx4 v[26:29], v[26:27], off
	s_nop 0
	v_addc_co_u32_e32 v31, vcc, 0, v63, vcc
	v_add_co_u32_e32 v40, vcc, s70, v62
	global_load_dwordx4 v[30:33], v[30:31], off
	s_nop 0
	v_addc_co_u32_e32 v41, vcc, 0, v63, vcc
	v_add_co_u32_e32 v44, vcc, s71, v62
	global_load_dwordx4 v[40:43], v[40:41], off
	s_nop 0
	v_addc_co_u32_e32 v45, vcc, 0, v63, vcc
	v_add_co_u32_e32 v50, vcc, s72, v62
	global_load_dwordx4 v[44:47], v[44:45], off
	s_nop 0
	v_addc_co_u32_e32 v51, vcc, 0, v63, vcc
	v_add_co_u32_e32 v54, vcc, s73, v62
	global_load_dwordx4 v[50:53], v[50:51], off
	s_nop 0
	v_addc_co_u32_e32 v55, vcc, 0, v63, vcc
	global_load_dwordx4 v[54:57], v[54:55], off
	v_add_u32_e32 v0, 0x600, v0
	v_ashrrev_i32_e32 v0, 6, v0
	s_waitcnt vmcnt(11)
	v_lshlrev_b32_e32 v58, 16, v4
	v_and_b32_e32 v59, 0xffff0000, v4
	v_lshlrev_b32_e32 v60, 16, v5
	v_and_b32_e32 v61, 0xffff0000, v5
	global_load_dwordx4 v[2:5], v[62:63], off
	s_waitcnt vmcnt(0)
	v_pk_add_f32 v[2:3], v[2:3], v[58:59]
	v_pk_add_f32 v[4:5], v[4:5], v[60:61]
	v_pk_add_f32 v[2:3], v[6:7], v[2:3]
	v_pk_add_f32 v[4:5], v[8:9], v[4:5]
	v_pk_add_f32 v[2:3], v[10:11], v[2:3]
	v_pk_add_f32 v[4:5], v[12:13], v[4:5]
	v_pk_add_f32 v[2:3], v[14:15], v[2:3]
	v_pk_add_f32 v[4:5], v[16:17], v[4:5]
	v_pk_add_f32 v[2:3], v[18:19], v[2:3]
	v_pk_add_f32 v[4:5], v[20:21], v[4:5]
	v_pk_add_f32 v[2:3], v[22:23], v[2:3]
	v_pk_add_f32 v[4:5], v[24:25], v[4:5]
	v_pk_add_f32 v[2:3], v[26:27], v[2:3]
	v_pk_add_f32 v[4:5], v[28:29], v[4:5]
	v_pk_add_f32 v[2:3], v[30:31], v[2:3]
	v_pk_add_f32 v[4:5], v[32:33], v[4:5]
	v_pk_add_f32 v[2:3], v[40:41], v[2:3]
	v_pk_add_f32 v[4:5], v[42:43], v[4:5]
	v_pk_add_f32 v[2:3], v[44:45], v[2:3]
	v_pk_add_f32 v[4:5], v[46:47], v[4:5]
	v_pk_add_f32 v[2:3], v[50:51], v[2:3]
	v_pk_add_f32 v[4:5], v[52:53], v[4:5]
	v_pk_add_f32 v[52:53], v[54:55], v[2:3]
	v_add_co_u32_e32 v2, vcc, s74, v62
	v_pk_add_f32 v[50:51], v[56:57], v[4:5]
	s_nop 0
	v_addc_co_u32_e32 v3, vcc, 0, v63, vcc
	v_add_co_u32_e32 v6, vcc, s75, v62
	global_load_dwordx4 v[2:5], v[2:3], off
	s_nop 0
	v_addc_co_u32_e32 v7, vcc, 0, v63, vcc
	v_add_co_u32_e32 v10, vcc, s76, v62
	global_load_dwordx4 v[6:9], v[6:7], off
	s_nop 0
	v_addc_co_u32_e32 v11, vcc, 0, v63, vcc
	v_add_co_u32_e32 v14, vcc, s77, v62
	global_load_dwordx4 v[10:13], v[10:11], off
	s_nop 0
	v_addc_co_u32_e32 v15, vcc, 0, v63, vcc
	v_add_co_u32_e32 v18, vcc, s78, v62
	global_load_dwordx4 v[14:17], v[14:15], off
	s_nop 0
	v_addc_co_u32_e32 v19, vcc, 0, v63, vcc
	v_add_co_u32_e32 v22, vcc, s79, v62
	global_load_dwordx4 v[18:21], v[18:19], off
	s_nop 0
	v_addc_co_u32_e32 v23, vcc, 0, v63, vcc
	v_add_co_u32_e32 v26, vcc, s80, v62
	global_load_dwordx4 v[22:25], v[22:23], off
	s_nop 0
	v_addc_co_u32_e32 v27, vcc, 0, v63, vcc
	v_add_co_u32_e32 v30, vcc, s81, v62
	global_load_dwordx4 v[26:29], v[26:27], off
	s_nop 0
	v_addc_co_u32_e32 v31, vcc, 0, v63, vcc
	v_add_co_u32_e32 v40, vcc, s82, v62
	global_load_dwordx4 v[30:33], v[30:31], off
	s_nop 0
	v_addc_co_u32_e32 v41, vcc, 0, v63, vcc
	v_add_co_u32_e32 v44, vcc, s83, v62
	global_load_dwordx4 v[40:43], v[40:41], off
	s_nop 0
	v_addc_co_u32_e32 v45, vcc, 0, v63, vcc
	global_load_dwordx4 v[44:47], v[44:45], off
	s_waitcnt vmcnt(9)
	v_pk_add_f32 v[4:5], v[4:5], v[50:51]
	v_pk_add_f32 v[2:3], v[2:3], v[52:53]
	s_waitcnt vmcnt(8)
	v_pk_add_f32 v[4:5], v[8:9], v[4:5]
	v_pk_add_f32 v[2:3], v[6:7], v[2:3]
	v_lshl_add_u64 v[6:7], v[34:35], 2, s[68:69]
	s_waitcnt vmcnt(7)
	v_pk_add_f32 v[4:5], v[12:13], v[4:5]
	v_pk_add_f32 v[2:3], v[10:11], v[2:3]
	s_waitcnt vmcnt(6)
	v_pk_add_f32 v[4:5], v[16:17], v[4:5]
	v_pk_add_f32 v[2:3], v[14:15], v[2:3]
	s_waitcnt vmcnt(5)
	v_pk_add_f32 v[4:5], v[20:21], v[4:5]
	v_pk_add_f32 v[2:3], v[18:19], v[2:3]
	s_waitcnt vmcnt(4)
	v_pk_add_f32 v[4:5], v[24:25], v[4:5]
	v_pk_add_f32 v[2:3], v[22:23], v[2:3]
	s_waitcnt vmcnt(3)
	v_pk_add_f32 v[4:5], v[28:29], v[4:5]
	v_pk_add_f32 v[2:3], v[26:27], v[2:3]
	s_waitcnt vmcnt(2)
	v_pk_add_f32 v[4:5], v[32:33], v[4:5]
	v_pk_add_f32 v[2:3], v[30:31], v[2:3]
	s_waitcnt vmcnt(1)
	v_pk_add_f32 v[4:5], v[42:43], v[4:5]
	v_pk_add_f32 v[2:3], v[40:41], v[2:3]
	s_waitcnt vmcnt(0)
	v_pk_add_f32 v[4:5], v[46:47], v[4:5]
	v_pk_add_f32 v[2:3], v[44:45], v[2:3]
	global_store_dwordx4 v[6:7], v[2:5], off
	s_nop 1
	v_ashrrev_i32_e32 v2, 6, v1
	v_ashrrev_i32_e32 v3, 31, v2
	v_lshlrev_b64 v[4:5], 11, v[2:3]
	v_lshl_add_u64 v[4:5], v[4:5], 0, v[36:37]
	v_lshl_add_u64 v[34:35], v[4:5], 0, s[26:27]
	v_lshl_add_u64 v[4:5], v[34:35], 1, s[4:5]
	global_load_dwordx2 v[4:5], v[4:5], off
	v_lshlrev_b64 v[2:3], 13, v[2:3]
	v_lshl_add_u64 v[62:63], v[38:39], 0, v[2:3]
	v_add_co_u32_e32 v6, vcc, s61, v62
	v_ashrrev_i32_e32 v1, 31, v0
	s_nop 0
	v_addc_co_u32_e32 v7, vcc, 0, v63, vcc
	v_add_co_u32_e32 v10, vcc, s62, v62
	global_load_dwordx4 v[6:9], v[6:7], off
	s_nop 0
	v_addc_co_u32_e32 v11, vcc, 0, v63, vcc
	v_add_co_u32_e32 v14, vcc, s63, v62
	global_load_dwordx4 v[10:13], v[10:11], off
	s_nop 0
	v_addc_co_u32_e32 v15, vcc, 0, v63, vcc
	v_add_co_u32_e32 v18, vcc, s64, v62
	global_load_dwordx4 v[14:17], v[14:15], off
	s_nop 0
	v_addc_co_u32_e32 v19, vcc, 0, v63, vcc
	v_add_co_u32_e32 v22, vcc, s65, v62
	global_load_dwordx4 v[18:21], v[18:19], off
	s_nop 0
	v_addc_co_u32_e32 v23, vcc, 0, v63, vcc
	v_add_co_u32_e32 v26, vcc, s66, v62
	global_load_dwordx4 v[22:25], v[22:23], off
	s_nop 0
	v_addc_co_u32_e32 v27, vcc, 0, v63, vcc
	v_add_co_u32_e32 v30, vcc, s67, v62
	global_load_dwordx4 v[26:29], v[26:27], off
	s_nop 0
	v_addc_co_u32_e32 v31, vcc, 0, v63, vcc
	v_add_co_u32_e32 v40, vcc, s70, v62
	global_load_dwordx4 v[30:33], v[30:31], off
	s_nop 0
	v_addc_co_u32_e32 v41, vcc, 0, v63, vcc
	v_add_co_u32_e32 v44, vcc, s71, v62
	global_load_dwordx4 v[40:43], v[40:41], off
	s_nop 0
	v_addc_co_u32_e32 v45, vcc, 0, v63, vcc
	v_add_co_u32_e32 v50, vcc, s72, v62
	global_load_dwordx4 v[44:47], v[44:45], off
	s_nop 0
	v_addc_co_u32_e32 v51, vcc, 0, v63, vcc
	v_add_co_u32_e32 v54, vcc, s73, v62
	global_load_dwordx4 v[50:53], v[50:51], off
	s_nop 0
	v_addc_co_u32_e32 v55, vcc, 0, v63, vcc
	global_load_dwordx4 v[54:57], v[54:55], off
	s_waitcnt vmcnt(11)
	v_lshlrev_b32_e32 v58, 16, v4
	v_and_b32_e32 v59, 0xffff0000, v4
	v_lshlrev_b32_e32 v60, 16, v5
	v_and_b32_e32 v61, 0xffff0000, v5
	global_load_dwordx4 v[2:5], v[62:63], off
	s_waitcnt vmcnt(0)
	v_pk_add_f32 v[2:3], v[2:3], v[58:59]
	v_pk_add_f32 v[4:5], v[4:5], v[60:61]
	v_pk_add_f32 v[2:3], v[6:7], v[2:3]
	v_pk_add_f32 v[4:5], v[8:9], v[4:5]
	v_pk_add_f32 v[2:3], v[10:11], v[2:3]
	v_pk_add_f32 v[4:5], v[12:13], v[4:5]
	v_pk_add_f32 v[2:3], v[14:15], v[2:3]
	v_pk_add_f32 v[4:5], v[16:17], v[4:5]
	v_pk_add_f32 v[2:3], v[18:19], v[2:3]
	v_pk_add_f32 v[4:5], v[20:21], v[4:5]
	v_pk_add_f32 v[2:3], v[22:23], v[2:3]
	v_pk_add_f32 v[4:5], v[24:25], v[4:5]
	v_pk_add_f32 v[2:3], v[26:27], v[2:3]
	v_pk_add_f32 v[4:5], v[28:29], v[4:5]
	v_pk_add_f32 v[2:3], v[30:31], v[2:3]
	v_pk_add_f32 v[4:5], v[32:33], v[4:5]
	v_pk_add_f32 v[2:3], v[40:41], v[2:3]
	v_pk_add_f32 v[4:5], v[42:43], v[4:5]
	v_pk_add_f32 v[2:3], v[44:45], v[2:3]
	v_pk_add_f32 v[4:5], v[46:47], v[4:5]
	v_pk_add_f32 v[2:3], v[50:51], v[2:3]
	v_pk_add_f32 v[4:5], v[52:53], v[4:5]
	v_pk_add_f32 v[52:53], v[54:55], v[2:3]
	v_add_co_u32_e32 v2, vcc, s74, v62
	v_pk_add_f32 v[50:51], v[56:57], v[4:5]
	s_nop 0
	v_addc_co_u32_e32 v3, vcc, 0, v63, vcc
	v_add_co_u32_e32 v6, vcc, s75, v62
	global_load_dwordx4 v[2:5], v[2:3], off
	s_nop 0
	v_addc_co_u32_e32 v7, vcc, 0, v63, vcc
	v_add_co_u32_e32 v10, vcc, s76, v62
	global_load_dwordx4 v[6:9], v[6:7], off
	s_nop 0
	v_addc_co_u32_e32 v11, vcc, 0, v63, vcc
	v_add_co_u32_e32 v14, vcc, s77, v62
	global_load_dwordx4 v[10:13], v[10:11], off
	s_nop 0
	v_addc_co_u32_e32 v15, vcc, 0, v63, vcc
	v_add_co_u32_e32 v18, vcc, s78, v62
	global_load_dwordx4 v[14:17], v[14:15], off
	s_nop 0
	v_addc_co_u32_e32 v19, vcc, 0, v63, vcc
	v_add_co_u32_e32 v22, vcc, s79, v62
	global_load_dwordx4 v[18:21], v[18:19], off
	s_nop 0
	v_addc_co_u32_e32 v23, vcc, 0, v63, vcc
	v_add_co_u32_e32 v26, vcc, s80, v62
	global_load_dwordx4 v[22:25], v[22:23], off
	s_nop 0
	v_addc_co_u32_e32 v27, vcc, 0, v63, vcc
	v_add_co_u32_e32 v30, vcc, s81, v62
	global_load_dwordx4 v[26:29], v[26:27], off
	s_nop 0
	v_addc_co_u32_e32 v31, vcc, 0, v63, vcc
	v_add_co_u32_e32 v40, vcc, s82, v62
	global_load_dwordx4 v[30:33], v[30:31], off
	s_nop 0
	v_addc_co_u32_e32 v41, vcc, 0, v63, vcc
	v_add_co_u32_e32 v44, vcc, s83, v62
	global_load_dwordx4 v[40:43], v[40:41], off
	s_nop 0
	v_addc_co_u32_e32 v45, vcc, 0, v63, vcc
	global_load_dwordx4 v[44:47], v[44:45], off
	s_waitcnt vmcnt(9)
	v_pk_add_f32 v[4:5], v[4:5], v[50:51]
	v_pk_add_f32 v[2:3], v[2:3], v[52:53]
	s_waitcnt vmcnt(8)
	v_pk_add_f32 v[4:5], v[8:9], v[4:5]
	v_pk_add_f32 v[2:3], v[6:7], v[2:3]
	v_lshl_add_u64 v[6:7], v[34:35], 2, s[68:69]
	s_waitcnt vmcnt(7)
	v_pk_add_f32 v[4:5], v[12:13], v[4:5]
	v_pk_add_f32 v[2:3], v[10:11], v[2:3]
	s_waitcnt vmcnt(6)
	v_pk_add_f32 v[4:5], v[16:17], v[4:5]
	v_pk_add_f32 v[2:3], v[14:15], v[2:3]
	s_waitcnt vmcnt(5)
	v_pk_add_f32 v[4:5], v[20:21], v[4:5]
	v_pk_add_f32 v[2:3], v[18:19], v[2:3]
	s_waitcnt vmcnt(4)
	v_pk_add_f32 v[4:5], v[24:25], v[4:5]
	v_pk_add_f32 v[2:3], v[22:23], v[2:3]
	s_waitcnt vmcnt(3)
	v_pk_add_f32 v[4:5], v[28:29], v[4:5]
	v_pk_add_f32 v[2:3], v[26:27], v[2:3]
	s_waitcnt vmcnt(2)
	v_pk_add_f32 v[4:5], v[32:33], v[4:5]
	v_pk_add_f32 v[2:3], v[30:31], v[2:3]
	s_waitcnt vmcnt(1)
	v_pk_add_f32 v[4:5], v[42:43], v[4:5]
	v_pk_add_f32 v[2:3], v[40:41], v[2:3]
	s_waitcnt vmcnt(0)
	v_pk_add_f32 v[4:5], v[46:47], v[4:5]
	v_pk_add_f32 v[2:3], v[44:45], v[2:3]
	global_store_dwordx4 v[6:7], v[2:5], off
	s_nop 1
	v_lshlrev_b64 v[2:3], 11, v[0:1]
	v_lshl_add_u64 v[2:3], v[2:3], 0, v[36:37]
	v_lshl_add_u64 v[40:41], v[2:3], 0, s[26:27]
	v_lshl_add_u64 v[2:3], v[40:41], 1, s[4:5]
	global_load_dwordx2 v[2:3], v[2:3], off
	v_lshlrev_b64 v[0:1], 13, v[0:1]
	v_lshl_add_u64 v[42:43], v[38:39], 0, v[0:1]
	v_add_co_u32_e32 v8, vcc, s61, v42
	s_nop 1
	v_addc_co_u32_e32 v9, vcc, 0, v43, vcc
	v_add_co_u32_e32 v12, vcc, s62, v42
	global_load_dwordx4 v[8:11], v[8:9], off
	s_nop 0
	v_addc_co_u32_e32 v13, vcc, 0, v43, vcc
	v_add_co_u32_e32 v16, vcc, s63, v42
	global_load_dwordx4 v[12:15], v[12:13], off
	s_nop 0
	v_addc_co_u32_e32 v17, vcc, 0, v43, vcc
	v_add_co_u32_e32 v20, vcc, s64, v42
	global_load_dwordx4 v[16:19], v[16:17], off
	s_nop 0
	v_addc_co_u32_e32 v21, vcc, 0, v43, vcc
	v_add_co_u32_e32 v24, vcc, s65, v42
	global_load_dwordx4 v[20:23], v[20:21], off
	s_nop 0
	v_addc_co_u32_e32 v25, vcc, 0, v43, vcc
	v_add_co_u32_e32 v28, vcc, s66, v42
	global_load_dwordx4 v[24:27], v[24:25], off
	s_nop 0
	v_addc_co_u32_e32 v29, vcc, 0, v43, vcc
	v_add_co_u32_e32 v32, vcc, s67, v42
	global_load_dwordx4 v[28:31], v[28:29], off
	s_nop 0
	v_addc_co_u32_e32 v33, vcc, 0, v43, vcc
	v_add_co_u32_e32 v44, vcc, s70, v42
	global_load_dwordx4 v[32:35], v[32:33], off
	s_nop 0
	v_addc_co_u32_e32 v45, vcc, 0, v43, vcc
	v_add_co_u32_e32 v50, vcc, s71, v42
	global_load_dwordx4 v[44:47], v[44:45], off
	s_nop 0
	v_addc_co_u32_e32 v51, vcc, 0, v43, vcc
	v_add_co_u32_e32 v54, vcc, s72, v42
	global_load_dwordx4 v[50:53], v[50:51], off
	s_nop 0
	v_addc_co_u32_e32 v55, vcc, 0, v43, vcc
	v_add_co_u32_e32 v58, vcc, s73, v42
	global_load_dwordx4 v[54:57], v[54:55], off
	s_nop 0
	v_addc_co_u32_e32 v59, vcc, 0, v43, vcc
	global_load_dwordx4 v[58:61], v[58:59], off
	s_waitcnt vmcnt(11)
	v_lshlrev_b32_e32 v4, 16, v2
	v_and_b32_e32 v5, 0xffff0000, v2
	v_lshlrev_b32_e32 v6, 16, v3
	v_and_b32_e32 v7, 0xffff0000, v3
	global_load_dwordx4 v[0:3], v[42:43], off
	s_waitcnt vmcnt(0)
	v_pk_add_f32 v[0:1], v[0:1], v[4:5]
	s_nop 0
	v_pk_add_f32 v[0:1], v[8:9], v[0:1]
	v_pk_add_f32 v[2:3], v[2:3], v[6:7]
	v_pk_add_f32 v[0:1], v[12:13], v[0:1]
	v_pk_add_f32 v[2:3], v[10:11], v[2:3]
	v_pk_add_f32 v[0:1], v[16:17], v[0:1]
	v_pk_add_f32 v[2:3], v[14:15], v[2:3]
	v_pk_add_f32 v[0:1], v[20:21], v[0:1]
	v_pk_add_f32 v[2:3], v[18:19], v[2:3]
	v_pk_add_f32 v[0:1], v[24:25], v[0:1]
	v_pk_add_f32 v[2:3], v[22:23], v[2:3]
	v_pk_add_f32 v[0:1], v[28:29], v[0:1]
	v_pk_add_f32 v[2:3], v[26:27], v[2:3]
	v_pk_add_f32 v[0:1], v[32:33], v[0:1]
	v_pk_add_f32 v[2:3], v[30:31], v[2:3]
	v_pk_add_f32 v[0:1], v[44:45], v[0:1]
	v_pk_add_f32 v[2:3], v[34:35], v[2:3]
	v_pk_add_f32 v[0:1], v[50:51], v[0:1]
	v_pk_add_f32 v[2:3], v[46:47], v[2:3]
	v_pk_add_f32 v[0:1], v[54:55], v[0:1]
	v_pk_add_f32 v[2:3], v[52:53], v[2:3]
	v_pk_add_f32 v[46:47], v[58:59], v[0:1]
	v_add_co_u32_e32 v0, vcc, s74, v42
	v_pk_add_f32 v[2:3], v[56:57], v[2:3]
	s_nop 0
	v_addc_co_u32_e32 v1, vcc, 0, v43, vcc
	v_add_co_u32_e32 v4, vcc, s75, v42
	v_pk_add_f32 v[44:45], v[60:61], v[2:3]
	s_nop 0
	v_addc_co_u32_e32 v5, vcc, 0, v43, vcc
	v_add_co_u32_e32 v8, vcc, s76, v42
	global_load_dwordx4 v[0:3], v[0:1], off
	s_nop 0
	v_addc_co_u32_e32 v9, vcc, 0, v43, vcc
	v_add_co_u32_e32 v12, vcc, s77, v42
	global_load_dwordx4 v[4:7], v[4:5], off
	s_nop 0
	v_addc_co_u32_e32 v13, vcc, 0, v43, vcc
	v_add_co_u32_e32 v16, vcc, s78, v42
	global_load_dwordx4 v[8:11], v[8:9], off
	s_nop 0
	v_addc_co_u32_e32 v17, vcc, 0, v43, vcc
	v_add_co_u32_e32 v20, vcc, s79, v42
	global_load_dwordx4 v[12:15], v[12:13], off
	s_nop 0
	v_addc_co_u32_e32 v21, vcc, 0, v43, vcc
	v_add_co_u32_e32 v24, vcc, s80, v42
	global_load_dwordx4 v[16:19], v[16:17], off
	s_nop 0
	v_addc_co_u32_e32 v25, vcc, 0, v43, vcc
	v_add_co_u32_e32 v28, vcc, s81, v42
	global_load_dwordx4 v[20:23], v[20:21], off
	s_nop 0
	v_addc_co_u32_e32 v29, vcc, 0, v43, vcc
	v_add_co_u32_e32 v32, vcc, s82, v42
	global_load_dwordx4 v[24:27], v[24:25], off
	s_nop 0
	v_addc_co_u32_e32 v33, vcc, 0, v43, vcc
	global_load_dwordx4 v[28:31], v[28:29], off
	v_add_co_u32_e32 v42, vcc, s83, v42
	global_load_dwordx4 v[32:35], v[32:33], off
	s_nop 0
	v_addc_co_u32_e32 v43, vcc, 0, v43, vcc
	global_load_dwordx4 v[50:53], v[42:43], off
	s_waitcnt vmcnt(9)
	v_pk_add_f32 v[2:3], v[2:3], v[44:45]
	v_pk_add_f32 v[0:1], v[0:1], v[46:47]
	s_waitcnt vmcnt(8)
	v_pk_add_f32 v[2:3], v[6:7], v[2:3]
	v_pk_add_f32 v[0:1], v[4:5], v[0:1]
	v_lshl_add_u64 v[4:5], v[40:41], 2, s[68:69]
	s_waitcnt vmcnt(7)
	v_pk_add_f32 v[2:3], v[10:11], v[2:3]
	v_pk_add_f32 v[0:1], v[8:9], v[0:1]
	s_waitcnt vmcnt(6)
	v_pk_add_f32 v[2:3], v[14:15], v[2:3]
	v_pk_add_f32 v[0:1], v[12:13], v[0:1]
	s_waitcnt vmcnt(5)
	v_pk_add_f32 v[2:3], v[18:19], v[2:3]
	v_pk_add_f32 v[0:1], v[16:17], v[0:1]
	s_waitcnt vmcnt(4)
	v_pk_add_f32 v[2:3], v[22:23], v[2:3]
	v_pk_add_f32 v[0:1], v[20:21], v[0:1]
	s_waitcnt vmcnt(3)
	v_pk_add_f32 v[2:3], v[26:27], v[2:3]
	v_pk_add_f32 v[0:1], v[24:25], v[0:1]
	s_waitcnt vmcnt(2)
	v_pk_add_f32 v[2:3], v[30:31], v[2:3]
	v_pk_add_f32 v[0:1], v[28:29], v[0:1]
	s_waitcnt vmcnt(1)
	v_pk_add_f32 v[2:3], v[34:35], v[2:3]
	v_pk_add_f32 v[0:1], v[32:33], v[0:1]
	s_waitcnt vmcnt(0)
	v_pk_add_f32 v[2:3], v[52:53], v[2:3]
	v_pk_add_f32 v[0:1], v[50:51], v[0:1]
	global_store_dwordx4 v[4:5], v[0:3], off
	s_cbranch_scc0 .LBB0_1949
